# v1 batched prologue weight loads + removed per-phase s_setprio flips in both GEMM K-loops
# speedup vs baseline: 1.0249x; 1.0249x over previous
; template <int PART>
; __device__ __forceinline__ void prologue(const Params& p, LAS unsigned char* lds) {
;     ...
;     for (int it = IT_LO + gw; it < IT_HI; it += NGW) {
;         int r = it;
;         if (r < 2 * I_A) { const int i = r / I_A; r -= i * I_A; p0_transpose_item(p.w_in_a + (size_t)i * DM * NA, DM, NA, WinA + (size_t)i * NA * DM, p.norm_a + i * DM, true, scr, r, lane); continue; } r -= 2 * I_A;
;         if (r < 2 * I_B) { const int i = r / I_B; r -= i * I_B; p0_transpose_item(p.w_in_b + (size_t)i * DM * NB, DM, NB, WinB + (size_t)i * NB * DM, p.norm_b + i * DM, true, scr, r, lane); continue; } r -= 2 * I_B;
;         { const int layer = r / I_O; r -= layer * I_O; const float* W = (layer & 1) ? p.w_out_b + (size_t)(layer >> 1) * DM * DM : p.w_out_a + (size_t)(layer >> 1) * DM * DM;
;           p0_transpose_item(W, DM, DM, Wout + (size_t)layer * DM * DM, nullptr, false, scr, r, lane); }
.LBB0_33:
	s_andn2_b64 vcc, exec, s[0:1]
	s_cbranch_vccnz .LBB0_7
	s_andn2_b64 vcc, exec, s[12:13]
	s_mov_b32 s30, s42
	s_mov_b32 s31, s41
	s_mov_b32 s34, s36
	s_cbranch_vccz .LBB0_37
	s_branch .LBB0_6
.LBB0_36:
	s_add_i32 s34, s34, s37
	s_add_i32 s31, s31, s39
	s_add_i32 s30, s30, s43
	s_cmpk_gt_i32 s34, 0x26ff
	s_cbranch_scc1 .LBB0_6

; #define LAS __attribute__((address_space(3)))
; __device__ __forceinline__ unsigned pkbf(float lo, float hi) { f32x2v v = {lo, hi}; return __builtin_bit_cast(unsigned, __builtin_convertvector(v, bf2_t)); }
; __device__ __forceinline__ void p0_transpose_item(const float* W, int K, int N, bf16_t* WT, const float* gain, bool permute, LAS float* scr, int item, int lane) {
;     ...
;     for (int i = 0; i < 32; ++i) { const int kk = 2 * i + (lane >> 5); const float gk = gain ? gain[k0 + kk] : 1.0f; scr[kk * 33 + (lane & 31)] = W[(size_t)(k0 + kk) * N + n0 + (lane & 31)] * gk; }
;     asm volatile("s_waitcnt lgkmcnt(0)" ::: "memory");
;     const int c = lane & 7;
; #pragma unroll
;     for (int j = 0; j < 4; ++j) { const int n = (lane >> 3) + 8 * j; const int nsrc = (qkperm && n < 16) ? 4 * (n >> 3) + 8 * ((n >> 2) & 1) + (n & 3) : n; const LAS float* s = scr + (8 * c) * 33 + nsrc;
;         u32x4 o; o.x = pkbf(s[0 * 33], s[1 * 33]); o.y = pkbf(s[2 * 33], s[3 * 33]); o.z = pkbf(s[4 * 33], s[5 * 33]); o.w = pkbf(s[6 * 33], s[7 * 33]);
;         *(u32x4*)(WT + (size_t)(prow0 + n) * K + k0 + 8 * c) = o; }
; template <int PART>
; __device__ __forceinline__ void prologue(const Params& p, LAS unsigned char* lds) {
;     ...
;         if (r < 2 * I_A) { const int i = r / I_A; r -= i * I_A; p0_transpose_item(p.w_in_a + (size_t)i * DM * NA, DM, NA, WinA + (size_t)i * NA * DM, p.norm_a + i * DM, true, scr, r, lane); continue; } r -= 2 * I_A;
;         if (r < 2 * I_B) { const int i = r / I_B; r -= i * I_B; p0_transpose_item(p.w_in_b + (size_t)i * DM * NB, DM, NB, WinB + (size_t)i * NB * DM, p.norm_b + i * DM, true, scr, r, lane); continue; } r -= 2 * I_B;
.LBB0_43:
	v_readlane_b32 s52, v252, 0
	s_and_b64 s[24:25], s[22:23], exec
	s_cselect_b32 s1, 0x1000, 0
	v_readlane_b32 s66, v252, 14
	v_readlane_b32 s67, v252, 15
	s_add_u32 s28, s66, s1
	s_sext_i32_i16 s0, s0
	s_addc_u32 s29, s67, 0
	s_lshl_b32 s24, s0, 6
	v_readlane_b32 s53, v252, 1
	v_readlane_b32 s54, v252, 2
	v_readlane_b32 s55, v252, 3
	v_readlane_b32 s56, v252, 4
	v_readlane_b32 s57, v252, 5
	v_readlane_b32 s58, v252, 6
	v_readlane_b32 s59, v252, 7
	v_readlane_b32 s60, v252, 8
	v_readlane_b32 s61, v252, 9
	v_readlane_b32 s62, v252, 10
	v_readlane_b32 s63, v252, 11
	v_readlane_b32 s64, v252, 12
	v_readlane_b32 s65, v252, 13
	s_and_b64 s[46:47], s[22:23], exec
	s_cselect_b32 s21, 0x1600000, 0
	s_add_u32 s25, s72, s21
	s_addc_u32 s45, s73, 0
	s_ashr_i32 s21, s20, 31
	s_lshl_b64 s[46:47], s[20:21], 2
	s_add_u32 s46, s25, s46
	s_addc_u32 s47, s45, s47
	s_ashr_i32 s25, s24, 31
	s_lshl_b32 s0, s24, 2
	s_add_u32 s0, s28, s0
	s_addc_u32 s1, s29, 0
	v_lshlrev_b32_e32 v106, 2, v122
	s_and_b64 vcc, exec, s[14:15]
	s_cbranch_vccz .Lwb_nogain
	global_load_dwordx4 v[226:229], v106, s[0:1]
	global_load_dwordx4 v[230:233], v106, s[0:1] offset:16
	s_branch .Lwb_gain_done
.Lwb_nogain:
	v_mov_b32_e32 v226, 1.0
	v_mov_b32_e32 v227, 1.0
	v_mov_b32_e32 v228, 1.0
	v_mov_b32_e32 v229, 1.0
	v_mov_b32_e32 v230, 1.0
	v_mov_b32_e32 v231, 1.0
	v_mov_b32_e32 v232, 1.0
	v_mov_b32_e32 v233, 1.0
.Lwb_gain_done:
	s_movk_i32 s45, 0x5800
	v_lshlrev_b32_e32 v114, 2, v120
	v_or_b32_e32 v107, s24, v118
	v_mad_u32_u24 v107, v107, s45, v114
	global_load_dword v74, v107, s[46:47]
	v_or_b32_e32 v107, s24, v126
	v_mad_u32_u24 v107, v107, s45, v114
	global_load_dword v75, v107, s[46:47]
	v_or_b32_e32 v107, s24, v128
	v_mad_u32_u24 v107, v107, s45, v114
	global_load_dword v76, v107, s[46:47]
	v_or_b32_e32 v107, s24, v130
	v_mad_u32_u24 v107, v107, s45, v114
	global_load_dword v77, v107, s[46:47]
	v_or_b32_e32 v107, s24, v132
	v_mad_u32_u24 v107, v107, s45, v114
	global_load_dword v78, v107, s[46:47]
	v_or_b32_e32 v107, s24, v134
	v_mad_u32_u24 v107, v107, s45, v114
	global_load_dword v79, v107, s[46:47]
	v_or_b32_e32 v107, s24, v136
	v_mad_u32_u24 v107, v107, s45, v114
	global_load_dword v80, v107, s[46:47]
	v_or_b32_e32 v107, s24, v138
	v_mad_u32_u24 v107, v107, s45, v114
	global_load_dword v81, v107, s[46:47]
	v_or_b32_e32 v107, s24, v140
	v_mad_u32_u24 v107, v107, s45, v114
	global_load_dword v82, v107, s[46:47]
	v_or_b32_e32 v107, s24, v142
	v_mad_u32_u24 v107, v107, s45, v114
	global_load_dword v83, v107, s[46:47]
	v_or_b32_e32 v107, s24, v144
	v_mad_u32_u24 v107, v107, s45, v114
	global_load_dword v84, v107, s[46:47]
	v_or_b32_e32 v107, s24, v146
	v_mad_u32_u24 v107, v107, s45, v114
	global_load_dword v85, v107, s[46:47]
	v_or_b32_e32 v107, s24, v148
	v_mad_u32_u24 v107, v107, s45, v114
	global_load_dword v86, v107, s[46:47]
	v_or_b32_e32 v107, s24, v150
	v_mad_u32_u24 v107, v107, s45, v114
	global_load_dword v87, v107, s[46:47]
	v_or_b32_e32 v107, s24, v152
	v_mad_u32_u24 v107, v107, s45, v114
	global_load_dword v88, v107, s[46:47]
	v_or_b32_e32 v107, s24, v154
	v_mad_u32_u24 v107, v107, s45, v114
	global_load_dword v89, v107, s[46:47]
	v_or_b32_e32 v107, s24, v156
	v_mad_u32_u24 v107, v107, s45, v114
	global_load_dword v90, v107, s[46:47]
	v_or_b32_e32 v107, s24, v158
	v_mad_u32_u24 v107, v107, s45, v114
	global_load_dword v91, v107, s[46:47]
	v_or_b32_e32 v107, s24, v160
	v_mad_u32_u24 v107, v107, s45, v114
	global_load_dword v92, v107, s[46:47]
	v_or_b32_e32 v107, s24, v162
	v_mad_u32_u24 v107, v107, s45, v114
	global_load_dword v93, v107, s[46:47]
	v_or_b32_e32 v107, s24, v163
	v_mad_u32_u24 v107, v107, s45, v114
	global_load_dword v94, v107, s[46:47]
	v_or_b32_e32 v107, s24, v164
	v_mad_u32_u24 v107, v107, s45, v114
	global_load_dword v95, v107, s[46:47]
	v_or_b32_e32 v107, s24, v165
	v_mad_u32_u24 v107, v107, s45, v114
	global_load_dword v96, v107, s[46:47]
	v_or_b32_e32 v107, s24, v166
	v_mad_u32_u24 v107, v107, s45, v114
	global_load_dword v97, v107, s[46:47]
	v_or_b32_e32 v107, s24, v167
	v_mad_u32_u24 v107, v107, s45, v114
	global_load_dword v98, v107, s[46:47]
	v_or_b32_e32 v107, s24, v171
	v_mad_u32_u24 v107, v107, s45, v114
	global_load_dword v99, v107, s[46:47]
	v_or_b32_e32 v107, s24, v172
	v_mad_u32_u24 v107, v107, s45, v114
	global_load_dword v100, v107, s[46:47]
	v_or_b32_e32 v107, s24, v173
	v_mad_u32_u24 v107, v107, s45, v114
	global_load_dword v101, v107, s[46:47]
	v_or_b32_e32 v107, s24, v174
	v_mad_u32_u24 v107, v107, s45, v114
	global_load_dword v102, v107, s[46:47]
	v_or_b32_e32 v107, s24, v175
	v_mad_u32_u24 v107, v107, s45, v114
	global_load_dword v103, v107, s[46:47]
	v_or_b32_e32 v107, s24, v176
	v_mad_u32_u24 v107, v107, s45, v114
	global_load_dword v104, v107, s[46:47]
	v_or_b32_e32 v107, s24, v177
	v_mad_u32_u24 v107, v107, s45, v114
	global_load_dword v105, v107, s[46:47]
	s_bitcmp0_b32 s35, 0
	s_cselect_b64 s[0:1], -1, 0
	s_and_b64 vcc, s[0:1], s[26:27]
	s_and_b64 s[0:1], s[22:23], exec
	s_cselect_b32 s0, 0xb00000, 0
	s_add_u32 s21, s51, s0
	v_readlane_b32 s0, v252, 16
	s_addc_u32 s22, s0, 0
	s_lshl_b32 s23, s6, 7
	s_and_b32 s20, s20, 0xffffff00
	s_lshl_b32 s6, s6, 4
	s_and_b32 s23, s23, 0x80
	v_cndmask_b32_e32 v50, v168, v170, vcc
	s_and_b32 s6, s6, 0x60
	s_or_b32 s20, s20, s23
	v_lshl_add_u32 v63, v50, 2, v169
	v_cndmask_b32_e32 v50, v179, v182, vcc
	s_lshl_b64 s[0:1], s[24:25], 1
	s_or_b32 s6, s20, s6
	v_lshl_add_u32 v64, v50, 2, v169
	s_add_u32 s0, s21, s0
	v_or_b32_e32 v50, s6, v168
	v_lshlrev_b32_e32 v114, 1, v122
	s_addc_u32 s1, s22, s1
	v_ashrrev_i32_e32 v51, 31, v50
	v_lshl_add_u64 v[60:61], s[0:1], 0, v[114:115]
	v_lshlrev_b64 v[50:51], 11, v[50:51]
	v_or_b32_e32 v54, s6, v179
	v_or_b32_e32 v56, s6, v180
	v_or_b32_e32 v58, s6, v181
	v_lshl_add_u64 v[66:67], v[60:61], 0, v[50:51]
	v_ashrrev_i32_e32 v55, 31, v54
	v_ashrrev_i32_e32 v57, 31, v56
	v_ashrrev_i32_e32 v59, 31, v58
	v_lshlrev_b64 v[54:55], 11, v[54:55]
	v_lshlrev_b64 v[56:57], 11, v[56:57]
	v_lshlrev_b64 v[58:59], 11, v[58:59]
	v_lshl_add_u64 v[68:69], v[60:61], 0, v[54:55]
	v_lshl_add_u64 v[70:71], v[60:61], 0, v[56:57]
	v_lshl_add_u64 v[72:73], v[60:61], 0, v[58:59]
	v_add_u32_e32 v106, v121, v123
	s_waitcnt vmcnt(28)
; #define LAS __attribute__((address_space(3)))
; __device__ __forceinline__ unsigned pkbf(float lo, float hi) { f32x2v v = {lo, hi}; return __builtin_bit_cast(unsigned, __builtin_convertvector(v, bf2_t)); }
; __device__ __forceinline__ void p0_transpose_item(const float* W, int K, int N, bf16_t* WT, const float* gain, bool permute, LAS float* scr, int item, int lane) {
;     ...
;     for (int i = 0; i < 32; ++i) { const int kk = 2 * i + (lane >> 5); const float gk = gain ? gain[k0 + kk] : 1.0f; scr[kk * 33 + (lane & 31)] = W[(size_t)(k0 + kk) * N + n0 + (lane & 31)] * gk; }
;     asm volatile("s_waitcnt lgkmcnt(0)" ::: "memory");
;     const int c = lane & 7;
; #pragma unroll
;     for (int j = 0; j < 4; ++j) { const int n = (lane >> 3) + 8 * j; const int nsrc = (qkperm && n < 16) ? 4 * (n >> 3) + 8 * ((n >> 2) & 1) + (n & 3) : n; const LAS float* s = scr + (8 * c) * 33 + nsrc;
;         u32x4 o; o.x = pkbf(s[0 * 33], s[1 * 33]); o.y = pkbf(s[2 * 33], s[3 * 33]); o.z = pkbf(s[4 * 33], s[5 * 33]); o.w = pkbf(s[6 * 33], s[7 * 33]);
;         *(u32x4*)(WT + (size_t)(prow0 + n) * K + k0 + 8 * c) = o; }
;     asm volatile("s_waitcnt lgkmcnt(0)" ::: "memory");
	ds_write_b32 v106, v74
	ds_write_b32 v106, v75 offset:264
	ds_write_b32 v106, v76 offset:528
	ds_write_b32 v106, v77 offset:792
	s_waitcnt vmcnt(24)
	ds_write_b32 v106, v78 offset:1056
	ds_write_b32 v106, v79 offset:1320
	ds_write_b32 v106, v80 offset:1584
	ds_write_b32 v106, v81 offset:1848
	s_waitcnt vmcnt(20)
	ds_write_b32 v106, v82 offset:2112
	ds_write_b32 v106, v83 offset:2376
	ds_write_b32 v106, v84 offset:2640
	ds_write_b32 v106, v85 offset:2904
	s_waitcnt vmcnt(16)
	ds_write_b32 v106, v86 offset:3168
	ds_write_b32 v106, v87 offset:3432
	ds_write_b32 v106, v88 offset:3696
	ds_write_b32 v106, v89 offset:3960
	s_waitcnt vmcnt(12)
	ds_write_b32 v106, v90 offset:4224
	ds_write_b32 v106, v91 offset:4488
	ds_write_b32 v106, v92 offset:4752
	ds_write_b32 v106, v93 offset:5016
	s_waitcnt vmcnt(8)
	ds_write_b32 v106, v94 offset:5280
	ds_write_b32 v106, v95 offset:5544
	ds_write_b32 v106, v96 offset:5808
	ds_write_b32 v106, v97 offset:6072
	s_waitcnt vmcnt(4)
	ds_write_b32 v106, v98 offset:6336
	ds_write_b32 v106, v99 offset:6600
	ds_write_b32 v106, v100 offset:6864
	ds_write_b32 v106, v101 offset:7128
	s_waitcnt vmcnt(0)
	ds_write_b32 v106, v102 offset:7392
	ds_write_b32 v106, v103 offset:7656
	ds_write_b32 v106, v104 offset:7920
	ds_write_b32 v106, v105 offset:8184
	s_waitcnt lgkmcnt(0)
	ds_read2_b32 v[50:51], v63 offset1:33
	ds_read2_b32 v[52:53], v63 offset0:66 offset1:99
	ds_read2_b32 v[54:55], v63 offset0:132 offset1:165
	ds_read2_b32 v[56:57], v63 offset0:198 offset1:231
	ds_read2_b32 v[58:59], v64 offset1:33
	ds_read2_b32 v[60:61], v64 offset0:66 offset1:99
	ds_read2_b32 v[62:63], v64 offset0:132 offset1:165
	ds_read2_b32 v[64:65], v64 offset0:198 offset1:231
	ds_read2_b32 v[74:75], v178 offset0:49 offset1:57
	ds_read2_b32 v[76:77], v178 offset0:16 offset1:24
	ds_read2_b32 v[78:79], v178 offset0:82 offset1:90
	ds_read2_b32 v[80:81], v178 offset0:115 offset1:123
	ds_read2_b32 v[82:83], v178 offset0:148 offset1:156
	ds_read2_b32 v[84:85], v178 offset0:181 offset1:189
	ds_read2_b32 v[86:87], v178 offset0:214 offset1:222
	ds_read2_b32 v[88:89], v178 offset0:247 offset1:255
	s_waitcnt lgkmcnt(0)
	v_mul_f32_e32 v50, v226, v50
	v_mul_f32_e32 v51, v227, v51
	v_mul_f32_e32 v52, v228, v52
	v_mul_f32_e32 v53, v229, v53
	v_mul_f32_e32 v54, v230, v54
	v_mul_f32_e32 v55, v231, v55
	v_mul_f32_e32 v56, v232, v56
	v_mul_f32_e32 v57, v233, v57
	v_mul_f32_e32 v58, v226, v58
	v_mul_f32_e32 v59, v227, v59
	v_mul_f32_e32 v60, v228, v60
	v_mul_f32_e32 v61, v229, v61
	v_mul_f32_e32 v62, v230, v62
	v_mul_f32_e32 v63, v231, v63
	v_mul_f32_e32 v64, v232, v64
	v_mul_f32_e32 v65, v233, v65
	v_mul_f32_e32 v74, v227, v74
	v_mul_f32_e32 v75, v227, v75
	v_mul_f32_e32 v76, v226, v76
	v_mul_f32_e32 v77, v226, v77
	v_mul_f32_e32 v78, v228, v78
	v_mul_f32_e32 v79, v228, v79
	v_mul_f32_e32 v80, v229, v80
	v_mul_f32_e32 v81, v229, v81
	v_mul_f32_e32 v82, v230, v82
	v_mul_f32_e32 v83, v230, v83
	v_mul_f32_e32 v84, v231, v84
	v_mul_f32_e32 v85, v231, v85
	v_mul_f32_e32 v86, v232, v86
	v_mul_f32_e32 v87, v232, v87
	v_mul_f32_e32 v88, v233, v88
	v_mul_f32_e32 v89, v233, v89
	v_cvt_pk_bf16_f32 v50, v50, v51
	v_cvt_pk_bf16_f32 v51, v52, v53
	v_cvt_pk_bf16_f32 v52, v54, v55
	v_cvt_pk_bf16_f32 v53, v56, v57
	v_cvt_pk_bf16_f32 v54, v58, v59
	v_cvt_pk_bf16_f32 v55, v60, v61
	v_cvt_pk_bf16_f32 v56, v62, v63
	v_cvt_pk_bf16_f32 v57, v64, v65
	v_cvt_pk_bf16_f32 v58, v76, v74
	v_cvt_pk_bf16_f32 v59, v78, v80
	v_cvt_pk_bf16_f32 v60, v82, v84
	v_cvt_pk_bf16_f32 v61, v86, v88
	v_cvt_pk_bf16_f32 v62, v77, v75
	v_cvt_pk_bf16_f32 v63, v79, v81
	v_cvt_pk_bf16_f32 v64, v83, v85
	v_cvt_pk_bf16_f32 v65, v87, v89
	global_store_dwordx4 v[66:67], v[50:53], off
	global_store_dwordx4 v[68:69], v[54:57], off
	global_store_dwordx4 v[70:71], v[58:61], off
	global_store_dwordx4 v[72:73], v[62:65], off
	s_waitcnt lgkmcnt(0)

; __device__ __forceinline__ void p0_transpose_item(const float* W, int K, int N, bf16_t* WT, const float* gain, bool permute, LAS float* scr, int item, int lane) {
;     const int nblk = N / 32, kb = item / nblk, nb = item % nblk, k0 = 64 * kb, n0 = 32 * nb;
;     int prow0 = n0; bool qkperm = false;
;     if (permute) { const int pn = n0 >> 8, wc = (n0 >> 6) & 3, bj = (n0 >> 5) & 1; prow0 = 256 * pn + 128 * bj + 32 * wc;
;         const bool isqk = (N == NA) ? (n0 < 1152) : (n0 < 4608 && (n0 % 1536) < 1280);
;         qkperm = isqk && bj == 0; }
; #pragma unroll
;     for (int i = 0; i < 32; ++i) { const int kk = 2 * i + (lane >> 5); const float gk = gain ? gain[k0 + kk] : 1.0f; scr[kk * 33 + (lane & 31)] = W[(size_t)(k0 + kk) * N + n0 + (lane & 31)] * gk; }
; template <int PART>
; __device__ __forceinline__ void prologue(const Params& p, LAS unsigned char* lds) {
;     ...
;         if (r < 2 * I_A) { const int i = r / I_A; r -= i * I_A; p0_transpose_item(p.w_in_a + (size_t)i * DM * NA, DM, NA, WinA + (size_t)i * NA * DM, p.norm_a + i * DM, true, scr, r, lane); continue; } r -= 2 * I_A;
.LBB0_111:
	s_andn2_b64 vcc, exec, s[0:1]
	s_cbranch_vccnz .LBB0_36
	v_readlane_b32 s52, v252, 0
	v_readlane_b32 s53, v252, 1
	v_readlane_b32 s54, v252, 2
	v_readlane_b32 s55, v252, 3
	v_readlane_b32 s56, v252, 4
	v_readlane_b32 s57, v252, 5
	v_readlane_b32 s58, v252, 6
	v_readlane_b32 s59, v252, 7
	v_readlane_b32 s60, v252, 8
	v_readlane_b32 s61, v252, 9
	v_readlane_b32 s62, v252, 10
	v_readlane_b32 s63, v252, 11
	v_readlane_b32 s64, v252, 12
	v_readlane_b32 s65, v252, 13
	v_readlane_b32 s66, v252, 14
	v_readlane_b32 s67, v252, 15
	s_mul_hi_i32 s0, s34, 0x38e38e39
	s_lshr_b32 s1, s0, 31
	s_ashr_i32 s6, s0, 8
	s_add_i32 s6, s6, s1
	s_mul_i32 s0, s6, 0xfffffb80
	s_add_i32 s21, s34, s0
	s_lshl_b32 s0, s6, 10
	s_ashr_i32 s1, s0, 31
	s_lshl_b64 s[0:1], s[0:1], 2
	s_add_u32 s24, s54, s0
	s_mul_hi_i32 s0, s21, 0x38e38e39
	s_addc_u32 s25, s55, s1
	s_lshr_b32 s1, s0, 31
	s_ashr_i32 s22, s0, 4
	s_add_i32 s22, s22, s1
	s_lshl_b32 s20, s22, 6
	s_mul_i32 s26, s6, 0x900000
	s_mul_hi_i32 s23, s6, 0x900000
	s_add_u32 s27, s56, s26
	s_mulk_i32 s22, 0x48
	s_addc_u32 s35, s57, s23
	s_sub_i32 s26, s21, s22
	s_lshl_b32 s22, s26, 5
	s_ashr_i32 s23, s22, 31
	s_lshl_b64 s[28:29], s[22:23], 2
	s_add_u32 s28, s27, s28
	s_addc_u32 s29, s35, s29
	s_ashr_i32 s21, s20, 31
	s_lshl_b32 s0, s20, 2
	s_add_u32 s0, s24, s0
	s_addc_u32 s1, s25, 0
	v_lshlrev_b32_e32 v106, 2, v122
	s_and_b64 vcc, exec, s[16:17]
	s_cbranch_vccz .Lwa_nogain
	global_load_dwordx4 v[226:229], v106, s[0:1]
	global_load_dwordx4 v[230:233], v106, s[0:1] offset:16
	s_branch .Lwa_gain_done

; #define LAS __attribute__((address_space(3)))
; __device__ __forceinline__ unsigned pkbf(float lo, float hi) { f32x2v v = {lo, hi}; return __builtin_bit_cast(unsigned, __builtin_convertvector(v, bf2_t)); }
; __device__ __forceinline__ void p0_transpose_item(const float* W, int K, int N, bf16_t* WT, const float* gain, bool permute, LAS float* scr, int item, int lane) {
;     ...
;     if (permute) { const int pn = n0 >> 8, wc = (n0 >> 6) & 3, bj = (n0 >> 5) & 1; prow0 = 256 * pn + 128 * bj + 32 * wc;
;         const bool isqk = (N == NA) ? (n0 < 1152) : (n0 < 4608 && (n0 % 1536) < 1280);
;         qkperm = isqk && bj == 0; }
; #pragma unroll
;     for (int i = 0; i < 32; ++i) { const int kk = 2 * i + (lane >> 5); const float gk = gain ? gain[k0 + kk] : 1.0f; scr[kk * 33 + (lane & 31)] = W[(size_t)(k0 + kk) * N + n0 + (lane & 31)] * gk; }
;     asm volatile("s_waitcnt lgkmcnt(0)" ::: "memory");
;     const int c = lane & 7;
; #pragma unroll
;     for (int j = 0; j < 4; ++j) { const int n = (lane >> 3) + 8 * j; const int nsrc = (qkperm && n < 16) ? 4 * (n >> 3) + 8 * ((n >> 2) & 1) + (n & 3) : n; const LAS float* s = scr + (8 * c) * 33 + nsrc;
;         u32x4 o; o.x = pkbf(s[0 * 33], s[1 * 33]); o.y = pkbf(s[2 * 33], s[3 * 33]); o.z = pkbf(s[4 * 33], s[5 * 33]); o.w = pkbf(s[6 * 33], s[7 * 33]);
;         *(u32x4*)(WT + (size_t)(prow0 + n) * K + k0 + 8 * c) = o; }
.Lwa_gain_done:
	v_lshlrev_b32_e32 v114, 2, v120
	v_or_b32_e32 v107, s20, v118
	v_mad_u32_u24 v107, v107, s44, v114
	global_load_dword v74, v107, s[28:29]
	v_or_b32_e32 v107, s20, v126
	v_mad_u32_u24 v107, v107, s44, v114
	global_load_dword v75, v107, s[28:29]
	v_or_b32_e32 v107, s20, v128
	v_mad_u32_u24 v107, v107, s44, v114
	global_load_dword v76, v107, s[28:29]
	v_or_b32_e32 v107, s20, v130
	v_mad_u32_u24 v107, v107, s44, v114
	global_load_dword v77, v107, s[28:29]
	v_or_b32_e32 v107, s20, v132
	v_mad_u32_u24 v107, v107, s44, v114
	global_load_dword v78, v107, s[28:29]
	v_or_b32_e32 v107, s20, v134
	v_mad_u32_u24 v107, v107, s44, v114
	global_load_dword v79, v107, s[28:29]
	v_or_b32_e32 v107, s20, v136
	v_mad_u32_u24 v107, v107, s44, v114
	global_load_dword v80, v107, s[28:29]
	v_or_b32_e32 v107, s20, v138
	v_mad_u32_u24 v107, v107, s44, v114
	global_load_dword v81, v107, s[28:29]
	v_or_b32_e32 v107, s20, v140
	v_mad_u32_u24 v107, v107, s44, v114
	global_load_dword v82, v107, s[28:29]
	v_or_b32_e32 v107, s20, v142
	v_mad_u32_u24 v107, v107, s44, v114
	global_load_dword v83, v107, s[28:29]
	v_or_b32_e32 v107, s20, v144
	v_mad_u32_u24 v107, v107, s44, v114
	global_load_dword v84, v107, s[28:29]
	v_or_b32_e32 v107, s20, v146
	v_mad_u32_u24 v107, v107, s44, v114
	global_load_dword v85, v107, s[28:29]
	v_or_b32_e32 v107, s20, v148
	v_mad_u32_u24 v107, v107, s44, v114
	global_load_dword v86, v107, s[28:29]
	v_or_b32_e32 v107, s20, v150
	v_mad_u32_u24 v107, v107, s44, v114
	global_load_dword v87, v107, s[28:29]
	v_or_b32_e32 v107, s20, v152
	v_mad_u32_u24 v107, v107, s44, v114
	global_load_dword v88, v107, s[28:29]
	v_or_b32_e32 v107, s20, v154
	v_mad_u32_u24 v107, v107, s44, v114
	global_load_dword v89, v107, s[28:29]
	v_or_b32_e32 v107, s20, v156
	v_mad_u32_u24 v107, v107, s44, v114
	global_load_dword v90, v107, s[28:29]
	v_or_b32_e32 v107, s20, v158
	v_mad_u32_u24 v107, v107, s44, v114
	global_load_dword v91, v107, s[28:29]
	v_or_b32_e32 v107, s20, v160
	v_mad_u32_u24 v107, v107, s44, v114
	global_load_dword v92, v107, s[28:29]
	v_or_b32_e32 v107, s20, v162
	v_mad_u32_u24 v107, v107, s44, v114
	global_load_dword v93, v107, s[28:29]
	v_or_b32_e32 v107, s20, v163
	v_mad_u32_u24 v107, v107, s44, v114
	global_load_dword v94, v107, s[28:29]
	v_or_b32_e32 v107, s20, v164
	v_mad_u32_u24 v107, v107, s44, v114
	global_load_dword v95, v107, s[28:29]
	v_or_b32_e32 v107, s20, v165
	v_mad_u32_u24 v107, v107, s44, v114
	global_load_dword v96, v107, s[28:29]
	v_or_b32_e32 v107, s20, v166
	v_mad_u32_u24 v107, v107, s44, v114
	global_load_dword v97, v107, s[28:29]
	v_or_b32_e32 v107, s20, v167
	v_mad_u32_u24 v107, v107, s44, v114
	global_load_dword v98, v107, s[28:29]
	v_or_b32_e32 v107, s20, v171
	v_mad_u32_u24 v107, v107, s44, v114
	global_load_dword v99, v107, s[28:29]
	v_or_b32_e32 v107, s20, v172
	v_mad_u32_u24 v107, v107, s44, v114
	global_load_dword v100, v107, s[28:29]
	v_or_b32_e32 v107, s20, v173
	v_mad_u32_u24 v107, v107, s44, v114
	global_load_dword v101, v107, s[28:29]
	v_or_b32_e32 v107, s20, v174
	v_mad_u32_u24 v107, v107, s44, v114
	global_load_dword v102, v107, s[28:29]
	v_or_b32_e32 v107, s20, v175
	v_mad_u32_u24 v107, v107, s44, v114
	global_load_dword v103, v107, s[28:29]
	v_or_b32_e32 v107, s20, v176
	v_mad_u32_u24 v107, v107, s44, v114
	global_load_dword v104, v107, s[28:29]
	v_or_b32_e32 v107, s20, v177
	v_mad_u32_u24 v107, v107, s44, v114
	global_load_dword v105, v107, s[28:29]
	s_mul_hi_i32 s0, s6, 0x480000
	s_mul_i32 s6, s6, 0x480000
	s_add_u32 s6, s94, s6
	s_addc_u32 s24, s95, s0
	s_and_b32 s23, s26, 1
	s_and_b32 s0, s22, 0xffffff00
	s_lshl_b32 s1, s26, 4
	s_lshl_b32 s22, s23, 7
	s_and_b32 s1, s1, 0x60
	s_or_b32 s0, s0, s22
	s_or_b32 s0, s0, s1
	s_cmp_lt_i32 s26, 36
	v_or_b32_e32 v50, s0, v168
	v_or_b32_e32 v54, s0, v179
	v_or_b32_e32 v56, s0, v180
	v_or_b32_e32 v58, s0, v181
	s_cselect_b64 s[0:1], -1, 0
	s_cmp_eq_u32 s23, 0
	s_cselect_b64 s[22:23], -1, 0
	s_lshl_b64 s[20:21], s[20:21], 1
	s_and_b64 vcc, s[0:1], s[22:23]
	v_cndmask_b32_e32 v60, v168, v170, vcc
	s_add_u32 s0, s6, s20
	v_lshlrev_b32_e32 v114, 1, v122
	v_ashrrev_i32_e32 v51, 31, v50
	v_lshl_add_u32 v63, v60, 2, v169
	v_cndmask_b32_e32 v60, v179, v182, vcc
	s_addc_u32 s1, s24, s21
	v_lshlrev_b64 v[50:51], 11, v[50:51]
	v_lshl_add_u32 v64, v60, 2, v169
	v_lshl_add_u64 v[60:61], s[0:1], 0, v[114:115]
	v_lshl_add_u64 v[66:67], v[60:61], 0, v[50:51]
	v_ashrrev_i32_e32 v55, 31, v54
	v_ashrrev_i32_e32 v57, 31, v56
	v_ashrrev_i32_e32 v59, 31, v58
	v_lshlrev_b64 v[54:55], 11, v[54:55]
	v_lshlrev_b64 v[56:57], 11, v[56:57]
	v_lshlrev_b64 v[58:59], 11, v[58:59]
	v_lshl_add_u64 v[68:69], v[60:61], 0, v[54:55]
	v_lshl_add_u64 v[70:71], v[60:61], 0, v[56:57]
	v_lshl_add_u64 v[72:73], v[60:61], 0, v[58:59]
	v_add_u32_e32 v106, v121, v123
	s_waitcnt vmcnt(28)
; #define LAS __attribute__((address_space(3)))
; __device__ __forceinline__ unsigned pkbf(float lo, float hi) { f32x2v v = {lo, hi}; return __builtin_bit_cast(unsigned, __builtin_convertvector(v, bf2_t)); }
; __device__ __forceinline__ void p0_transpose_item(const float* W, int K, int N, bf16_t* WT, const float* gain, bool permute, LAS float* scr, int item, int lane) {
;     ...
;     for (int i = 0; i < 32; ++i) { const int kk = 2 * i + (lane >> 5); const float gk = gain ? gain[k0 + kk] : 1.0f; scr[kk * 33 + (lane & 31)] = W[(size_t)(k0 + kk) * N + n0 + (lane & 31)] * gk; }
;     asm volatile("s_waitcnt lgkmcnt(0)" ::: "memory");
;     const int c = lane & 7;
; #pragma unroll
;     for (int j = 0; j < 4; ++j) { const int n = (lane >> 3) + 8 * j; const int nsrc = (qkperm && n < 16) ? 4 * (n >> 3) + 8 * ((n >> 2) & 1) + (n & 3) : n; const LAS float* s = scr + (8 * c) * 33 + nsrc;
;         u32x4 o; o.x = pkbf(s[0 * 33], s[1 * 33]); o.y = pkbf(s[2 * 33], s[3 * 33]); o.z = pkbf(s[4 * 33], s[5 * 33]); o.w = pkbf(s[6 * 33], s[7 * 33]);
;         *(u32x4*)(WT + (size_t)(prow0 + n) * K + k0 + 8 * c) = o; }
;     asm volatile("s_waitcnt lgkmcnt(0)" ::: "memory");
	ds_write_b32 v106, v74
	ds_write_b32 v106, v75 offset:264
	ds_write_b32 v106, v76 offset:528
	ds_write_b32 v106, v77 offset:792
	s_waitcnt vmcnt(24)
	ds_write_b32 v106, v78 offset:1056
	ds_write_b32 v106, v79 offset:1320
	ds_write_b32 v106, v80 offset:1584
	ds_write_b32 v106, v81 offset:1848
	s_waitcnt vmcnt(20)
	ds_write_b32 v106, v82 offset:2112
	ds_write_b32 v106, v83 offset:2376
	ds_write_b32 v106, v84 offset:2640
	ds_write_b32 v106, v85 offset:2904
	s_waitcnt vmcnt(16)
	ds_write_b32 v106, v86 offset:3168
	ds_write_b32 v106, v87 offset:3432
	ds_write_b32 v106, v88 offset:3696
	ds_write_b32 v106, v89 offset:3960
	s_waitcnt vmcnt(12)
	ds_write_b32 v106, v90 offset:4224
	ds_write_b32 v106, v91 offset:4488
	ds_write_b32 v106, v92 offset:4752
	ds_write_b32 v106, v93 offset:5016
	s_waitcnt vmcnt(8)
	ds_write_b32 v106, v94 offset:5280
	ds_write_b32 v106, v95 offset:5544
	ds_write_b32 v106, v96 offset:5808
	ds_write_b32 v106, v97 offset:6072
	s_waitcnt vmcnt(4)
	ds_write_b32 v106, v98 offset:6336
	ds_write_b32 v106, v99 offset:6600
	ds_write_b32 v106, v100 offset:6864
	ds_write_b32 v106, v101 offset:7128
	s_waitcnt vmcnt(0)
	ds_write_b32 v106, v102 offset:7392
	ds_write_b32 v106, v103 offset:7656
	ds_write_b32 v106, v104 offset:7920
	ds_write_b32 v106, v105 offset:8184
	s_waitcnt lgkmcnt(0)
	ds_read2_b32 v[50:51], v63 offset1:33
	ds_read2_b32 v[52:53], v63 offset0:66 offset1:99
	ds_read2_b32 v[54:55], v63 offset0:132 offset1:165
	ds_read2_b32 v[56:57], v63 offset0:198 offset1:231
	ds_read2_b32 v[58:59], v64 offset1:33
	ds_read2_b32 v[60:61], v64 offset0:66 offset1:99
	ds_read2_b32 v[62:63], v64 offset0:132 offset1:165
	ds_read2_b32 v[64:65], v64 offset0:198 offset1:231
	ds_read2_b32 v[74:75], v178 offset0:49 offset1:57
	ds_read2_b32 v[76:77], v178 offset0:16 offset1:24
	ds_read2_b32 v[78:79], v178 offset0:82 offset1:90
	ds_read2_b32 v[80:81], v178 offset0:115 offset1:123
	ds_read2_b32 v[82:83], v178 offset0:148 offset1:156
	ds_read2_b32 v[84:85], v178 offset0:181 offset1:189
	ds_read2_b32 v[86:87], v178 offset0:214 offset1:222
	ds_read2_b32 v[88:89], v178 offset0:247 offset1:255
	s_waitcnt lgkmcnt(0)
	v_mul_f32_e32 v50, v226, v50
	v_mul_f32_e32 v51, v227, v51
	v_mul_f32_e32 v52, v228, v52
	v_mul_f32_e32 v53, v229, v53
	v_mul_f32_e32 v54, v230, v54
	v_mul_f32_e32 v55, v231, v55
	v_mul_f32_e32 v56, v232, v56
	v_mul_f32_e32 v57, v233, v57
	v_mul_f32_e32 v58, v226, v58
	v_mul_f32_e32 v59, v227, v59
	v_mul_f32_e32 v60, v228, v60
	v_mul_f32_e32 v61, v229, v61
	v_mul_f32_e32 v62, v230, v62
	v_mul_f32_e32 v63, v231, v63
	v_mul_f32_e32 v64, v232, v64
	v_mul_f32_e32 v65, v233, v65
	v_mul_f32_e32 v74, v227, v74
	v_mul_f32_e32 v75, v227, v75
	v_mul_f32_e32 v76, v226, v76
	v_mul_f32_e32 v77, v226, v77
	v_mul_f32_e32 v78, v228, v78
	v_mul_f32_e32 v79, v228, v79
	v_mul_f32_e32 v80, v229, v80
	v_mul_f32_e32 v81, v229, v81
	v_mul_f32_e32 v82, v230, v82
	v_mul_f32_e32 v83, v230, v83
	v_mul_f32_e32 v84, v231, v84
	v_mul_f32_e32 v85, v231, v85
	v_mul_f32_e32 v86, v232, v86
	v_mul_f32_e32 v87, v232, v87
	v_mul_f32_e32 v88, v233, v88
	v_mul_f32_e32 v89, v233, v89
	v_cvt_pk_bf16_f32 v50, v50, v51
	v_cvt_pk_bf16_f32 v51, v52, v53
	v_cvt_pk_bf16_f32 v52, v54, v55
	v_cvt_pk_bf16_f32 v53, v56, v57
	v_cvt_pk_bf16_f32 v54, v58, v59
	v_cvt_pk_bf16_f32 v55, v60, v61
	v_cvt_pk_bf16_f32 v56, v62, v63
	v_cvt_pk_bf16_f32 v57, v64, v65
	v_cvt_pk_bf16_f32 v58, v76, v74
	v_cvt_pk_bf16_f32 v59, v78, v80
	v_cvt_pk_bf16_f32 v60, v82, v84
	v_cvt_pk_bf16_f32 v61, v86, v88
	v_cvt_pk_bf16_f32 v62, v77, v75
	v_cvt_pk_bf16_f32 v63, v79, v81
	v_cvt_pk_bf16_f32 v64, v83, v85
	v_cvt_pk_bf16_f32 v65, v87, v89
	global_store_dwordx4 v[66:67], v[50:53], off
	global_store_dwordx4 v[68:69], v[54:57], off
	global_store_dwordx4 v[70:71], v[58:61], off
	global_store_dwordx4 v[72:73], v[62:65], off
	s_waitcnt lgkmcnt(0)
	s_branch .LBB0_36

; #define PG8_STAGE(bufoff, gbase, voff) do { _Pragma("unroll") for (int _i = 0; _i < 2; ++_i) \
;         __builtin_amdgcn_global_load_lds((const unsigned*)((const char*)(gbase) + (voff)[_i]), (PG8_LAS unsigned*)(lds + (bufoff) + ldsw + _i * 8192), 16, 0, 0); } while (0)
; #define PG8_LDA(dst, b, h) do { _Pragma("unroll") for (int m = 0; m < 4; ++m) _Pragma("unroll") for (int k = 0; k < 2; ++k) dst[m][k] = *(const PG8_LAS bf16x8*)(lds + PG8_SA(b, h) + aoff + m * 2048 + k * 1024); } while (0)
; #define PG8_LDB(dst, b, h) do { _Pragma("unroll") for (int n = 0; n < 2; ++n) _Pragma("unroll") for (int k = 0; k < 2; ++k) dst[n][k] = *(const PG8_LAS bf16x8*)(lds + PG8_SB(b, h) + boff + n * 2048 + k * 1024); } while (0)
; #define PG8_MMA(ai, bj, At, Bt) do { __builtin_amdgcn_s_setprio(1); _Pragma("unroll") for (int m = 0; m < 4; ++m) _Pragma("unroll") for (int n = 0; n < 2; ++n) _Pragma("unroll") for (int k = 0; k < 2; ++k) \
;         acc[ai][bj][m][n] = __builtin_amdgcn_mfma_f32_16x16x32_bf16(Bt[n][k], At[m][k], acc[ai][bj][m][n], 0, 0, 0); __builtin_amdgcn_s_setprio(0); } while (0)
; #define PG8_WAIT_V(n) asm volatile("s_waitcnt vmcnt(" #n ")" ::: "memory")
; #define PG8_WAIT_L(n) asm volatile("s_waitcnt lgkmcnt(" #n ")" ::: "memory")
; #define PG8_BAR __builtin_amdgcn_s_barrier()
; #define PG8_SCHED __builtin_amdgcn_sched_barrier(0)
; template <class Epi, class Sched, bool ALIGN_EPI = false, bool SP2 = false>
; __device__ __forceinline__ void gemm_phase(PG8_LAS unsigned char* lds, const Gemm g, const Sched& S, const Epi& E) {
;     ...
;             PG8_LDB(B0, 0, 0); PG8_LDB(B1, 0, 1); PG8_SCHED; PG8_LDA(At, 0, 0); PG8_STAGE(PG8_SA(1, 1), a1 + hstep, voffA);
;             PG8_WAIT_V(8); PG8_WAIT_L(0); PG8_BAR; PG8_MMA(0, 0, At, B0); PG8_MMA(0, 1, At, B1); PG8_BAR; PG8_SCHED;
;             PG8_LDA(At, 0, 1); PG8_STAGE(PG8_SB(0, 0), b2, voffB); PG8_STAGE(PG8_SB(0, 1), b2 + hstep, voffB); PG8_STAGE(PG8_SA(0, 0), a2, voffA);
.LBB0_300:
	s_add_u32 s30, s28, 0xfffc0080
	s_addc_u32 s31, s29, -1
	s_add_i32 s47, 0, 0x10000
	s_cmp_eq_u32 s46, 12
	s_cselect_b32 s43, s21, s31
	s_cselect_b32 s42, s27, s30
	v_add_u32_e32 v112, s47, v173
	s_cselect_b32 s31, s19, s45
	s_cselect_b32 s30, s35, s44
	s_add_i32 s50, 0, 0x14000
	ds_read_b128 v[130:133], v112
	ds_read_b128 v[134:137], v112 offset:1024
	ds_read_b128 v[138:141], v112 offset:2048
	ds_read_b128 v[142:145], v112 offset:3072
	v_add_u32_e32 v112, s50, v173
	ds_read_b128 v[146:149], v112
	ds_read_b128 v[150:153], v112 offset:1024
	ds_read_b128 v[192:195], v112 offset:2048
	ds_read_b128 v[206:209], v112 offset:3072
	v_lshl_add_u64 v[170:171], s[28:29], 0, v[166:167]
	s_add_i32 m0, s53, 0xc000
	ds_read_b128 v[210:213], v202
	ds_read_b128 v[214:217], v202 offset:1024
	ds_read_b128 v[218:221], v202 offset:2048
	ds_read_b128 v[222:225], v202 offset:3072
	ds_read_b128 v[226:229], v202 offset:4096
	ds_read_b128 v[230:233], v202 offset:5120
	ds_read_b128 v[234:237], v202 offset:6144
	ds_read_b128 v[238:241], v202 offset:7168
	global_load_lds_dwordx4 v[170:171], off
	v_lshl_add_u64 v[170:171], s[28:29], 0, v[168:169]
	s_add_i32 m0, s53, 0xe000
	s_nop 0
	global_load_lds_dwordx4 v[170:171], off
	s_waitcnt vmcnt(8)
	s_waitcnt lgkmcnt(0)
	s_barrier
	s_waitcnt lgkmcnt(0)
	v_mfma_f32_16x16x32_bf16 v[118:121], v[130:133], v[210:213], v[118:121]
	v_mfma_f32_16x16x32_bf16 v[114:117], v[138:141], v[210:213], v[114:117]
	v_mfma_f32_16x16x32_bf16 v[104:107], v[130:133], v[218:221], v[104:107]
	v_mfma_f32_16x16x32_bf16 v[96:99], v[138:141], v[218:221], v[96:99]
	v_mfma_f32_16x16x32_bf16 v[88:91], v[130:133], v[226:229], v[88:91]
	v_mfma_f32_16x16x32_bf16 v[80:83], v[138:141], v[226:229], v[80:83]
	v_mfma_f32_16x16x32_bf16 v[72:75], v[130:133], v[234:237], v[72:75]
	v_mfma_f32_16x16x32_bf16 v[64:67], v[138:141], v[234:237], v[64:67]
	v_mfma_f32_16x16x32_bf16 v[118:121], v[134:137], v[214:217], v[118:121]
	v_mfma_f32_16x16x32_bf16 v[114:117], v[142:145], v[214:217], v[114:117]
	v_mfma_f32_16x16x32_bf16 v[104:107], v[134:137], v[222:225], v[104:107]
	v_mfma_f32_16x16x32_bf16 v[96:99], v[142:145], v[222:225], v[96:99]
	v_mfma_f32_16x16x32_bf16 v[88:91], v[134:137], v[230:233], v[88:91]
	v_mfma_f32_16x16x32_bf16 v[80:83], v[142:145], v[230:233], v[80:83]
	v_mfma_f32_16x16x32_bf16 v[72:75], v[134:137], v[238:241], v[72:75]
	v_mfma_f32_16x16x32_bf16 v[64:67], v[142:145], v[238:241], v[64:67]
	v_mfma_f32_16x16x32_bf16 v[126:129], v[146:149], v[210:213], v[126:129]
	v_mfma_f32_16x16x32_bf16 v[122:125], v[192:195], v[210:213], v[122:125]
	v_mfma_f32_16x16x32_bf16 v[108:111], v[146:149], v[218:221], v[108:111]
	v_mfma_f32_16x16x32_bf16 v[100:103], v[192:195], v[218:221], v[100:103]
	v_mfma_f32_16x16x32_bf16 v[92:95], v[146:149], v[226:229], v[92:95]
	v_mfma_f32_16x16x32_bf16 v[84:87], v[192:195], v[226:229], v[84:87]
	v_mfma_f32_16x16x32_bf16 v[76:79], v[146:149], v[234:237], v[76:79]
	v_mfma_f32_16x16x32_bf16 v[68:71], v[192:195], v[234:237], v[68:71]
	v_mfma_f32_16x16x32_bf16 v[126:129], v[150:153], v[214:217], v[126:129]
	v_mfma_f32_16x16x32_bf16 v[122:125], v[206:209], v[214:217], v[122:125]
	v_mfma_f32_16x16x32_bf16 v[108:111], v[150:153], v[222:225], v[108:111]
	v_mfma_f32_16x16x32_bf16 v[100:103], v[206:209], v[222:225], v[100:103]
	v_mfma_f32_16x16x32_bf16 v[92:95], v[150:153], v[230:233], v[92:95]
	v_mfma_f32_16x16x32_bf16 v[84:87], v[206:209], v[230:233], v[84:87]
	v_mfma_f32_16x16x32_bf16 v[76:79], v[150:153], v[238:241], v[76:79]
	v_mfma_f32_16x16x32_bf16 v[68:71], v[206:209], v[238:241], v[68:71]
	s_barrier
	s_add_i32 s47, s47, s1
	v_lshl_add_u64 v[170:171], s[30:31], 0, v[156:157]
	s_mov_b32 m0, s47
	ds_read_b128 v[210:213], v202 offset:16384
	ds_read_b128 v[214:217], v202 offset:17408
	ds_read_b128 v[218:221], v202 offset:18432
	ds_read_b128 v[222:225], v202 offset:19456
	ds_read_b128 v[226:229], v202 offset:20480
	ds_read_b128 v[230:233], v202 offset:21504
	ds_read_b128 v[234:237], v202 offset:22528
	ds_read_b128 v[238:241], v202 offset:23552
	global_load_lds_dwordx4 v[170:171], off
	s_add_i32 m0, s47, 0x2000
	s_add_u32 s48, s30, 0x40000
	v_lshl_add_u64 v[242:243], s[30:31], 0, v[160:161]
	s_addc_u32 s49, s31, 0
	s_add_i32 s47, s50, s1
	global_load_lds_dwordx4 v[242:243], off
	v_lshl_add_u64 v[244:245], s[48:49], 0, v[156:157]
	s_mov_b32 m0, s47
	v_lshl_add_u64 v[246:247], s[42:43], 0, v[158:159]
	global_load_lds_dwordx4 v[244:245], off
	v_lshl_add_u64 v[244:245], s[48:49], 0, v[160:161]
	s_add_i32 m0, s47, 0x2000
	s_nop 0
	global_load_lds_dwordx4 v[244:245], off
	v_lshl_add_u64 v[244:245], s[42:43], 0, v[154:155]
	s_mov_b32 m0, s53
	s_nop 0
	global_load_lds_dwordx4 v[244:245], off
	s_mov_b32 m0, s54
	s_nop 0
	global_load_lds_dwordx4 v[246:247], off
	s_waitcnt vmcnt(8)
	s_waitcnt lgkmcnt(0)
	s_barrier
; #define PG8_STAGE(bufoff, gbase, voff) do { _Pragma("unroll") for (int _i = 0; _i < 2; ++_i) \
;         __builtin_amdgcn_global_load_lds((const unsigned*)((const char*)(gbase) + (voff)[_i]), (PG8_LAS unsigned*)(lds + (bufoff) + ldsw + _i * 8192), 16, 0, 0); } while (0)
; #define PG8_LDA(dst, b, h) do { _Pragma("unroll") for (int m = 0; m < 4; ++m) _Pragma("unroll") for (int k = 0; k < 2; ++k) dst[m][k] = *(const PG8_LAS bf16x8*)(lds + PG8_SA(b, h) + aoff + m * 2048 + k * 1024); } while (0)
; #define PG8_LDB(dst, b, h) do { _Pragma("unroll") for (int n = 0; n < 2; ++n) _Pragma("unroll") for (int k = 0; k < 2; ++k) dst[n][k] = *(const PG8_LAS bf16x8*)(lds + PG8_SB(b, h) + boff + n * 2048 + k * 1024); } while (0)
; #define PG8_MMA(ai, bj, At, Bt) do { __builtin_amdgcn_s_setprio(1); _Pragma("unroll") for (int m = 0; m < 4; ++m) _Pragma("unroll") for (int n = 0; n < 2; ++n) _Pragma("unroll") for (int k = 0; k < 2; ++k) \
;         acc[ai][bj][m][n] = __builtin_amdgcn_mfma_f32_16x16x32_bf16(Bt[n][k], At[m][k], acc[ai][bj][m][n], 0, 0, 0); __builtin_amdgcn_s_setprio(0); } while (0)
; #define PG8_WAIT_V(n) asm volatile("s_waitcnt vmcnt(" #n ")" ::: "memory")
; #define PG8_WAIT_L(n) asm volatile("s_waitcnt lgkmcnt(" #n ")" ::: "memory")
; #define PG8_BAR __builtin_amdgcn_s_barrier()
; #define PG8_SCHED __builtin_amdgcn_sched_barrier(0)
; template <class Epi, class Sched, bool ALIGN_EPI = false, bool SP2 = false>
; __device__ __forceinline__ void gemm_phase(PG8_LAS unsigned char* lds, const Gemm g, const Sched& S, const Epi& E) {
;     ...
;             PG8_WAIT_V(8); PG8_WAIT_L(0); PG8_BAR; PG8_MMA(1, 0, At, B0); PG8_MMA(1, 1, At, B1); PG8_BAR; PG8_SCHED;
;             PG8_LDB(B0, 1, 0); PG8_LDB(B1, 1, 1); PG8_SCHED; PG8_LDA(At, 1, 0); PG8_STAGE(PG8_SA(0, 1), a2 + hstep, voffA);
;             PG8_WAIT_V(8); PG8_WAIT_L(0); PG8_BAR; PG8_MMA(0, 0, At, B0); PG8_MMA(0, 1, At, B1); PG8_BAR; PG8_SCHED;
	s_waitcnt lgkmcnt(0)
	v_mfma_f32_16x16x32_bf16 v[56:59], v[130:133], v[210:213], v[56:59]
	v_mfma_f32_16x16x32_bf16 v[48:51], v[138:141], v[210:213], v[48:51]
	v_mfma_f32_16x16x32_bf16 v[40:43], v[130:133], v[218:221], v[40:43]
	v_mfma_f32_16x16x32_bf16 v[32:35], v[138:141], v[218:221], v[32:35]
	v_mfma_f32_16x16x32_bf16 v[24:27], v[130:133], v[226:229], v[24:27]
	v_mfma_f32_16x16x32_bf16 v[16:19], v[138:141], v[226:229], v[16:19]
	v_mfma_f32_16x16x32_bf16 v[12:15], v[130:133], v[234:237], v[12:15]
	v_mfma_f32_16x16x32_bf16 v[8:11], v[138:141], v[234:237], v[8:11]
	v_mfma_f32_16x16x32_bf16 v[56:59], v[134:137], v[214:217], v[56:59]
	v_mfma_f32_16x16x32_bf16 v[48:51], v[142:145], v[214:217], v[48:51]
	v_mfma_f32_16x16x32_bf16 v[40:43], v[134:137], v[222:225], v[40:43]
	v_mfma_f32_16x16x32_bf16 v[32:35], v[142:145], v[222:225], v[32:35]
	v_mfma_f32_16x16x32_bf16 v[24:27], v[134:137], v[230:233], v[24:27]
	v_mfma_f32_16x16x32_bf16 v[16:19], v[142:145], v[230:233], v[16:19]
	v_mfma_f32_16x16x32_bf16 v[12:15], v[134:137], v[238:241], v[12:15]
	v_mfma_f32_16x16x32_bf16 v[8:11], v[142:145], v[238:241], v[8:11]
	v_mfma_f32_16x16x32_bf16 v[60:63], v[146:149], v[210:213], v[60:63]
	v_mfma_f32_16x16x32_bf16 v[52:55], v[192:195], v[210:213], v[52:55]
	v_mfma_f32_16x16x32_bf16 v[44:47], v[146:149], v[218:221], v[44:47]
	v_mfma_f32_16x16x32_bf16 v[36:39], v[192:195], v[218:221], v[36:39]
	v_mfma_f32_16x16x32_bf16 v[28:31], v[146:149], v[226:229], v[28:31]
	v_mfma_f32_16x16x32_bf16 v[20:23], v[192:195], v[226:229], v[20:23]
	v_mfma_f32_16x16x32_bf16 v[4:7], v[146:149], v[234:237], v[4:7]
	v_mfma_f32_16x16x32_bf16 v[0:3], v[192:195], v[234:237], v[0:3]
	v_mfma_f32_16x16x32_bf16 v[60:63], v[150:153], v[214:217], v[60:63]
	v_mfma_f32_16x16x32_bf16 v[52:55], v[206:209], v[214:217], v[52:55]
	v_mfma_f32_16x16x32_bf16 v[44:47], v[150:153], v[222:225], v[44:47]
	v_mfma_f32_16x16x32_bf16 v[36:39], v[206:209], v[222:225], v[36:39]
	v_mfma_f32_16x16x32_bf16 v[28:31], v[150:153], v[230:233], v[28:31]
	v_mfma_f32_16x16x32_bf16 v[20:23], v[206:209], v[230:233], v[20:23]
	v_mfma_f32_16x16x32_bf16 v[4:7], v[150:153], v[238:241], v[4:7]
	v_mfma_f32_16x16x32_bf16 v[0:3], v[206:209], v[238:241], v[0:3]
	s_barrier
	s_add_i32 s47, 0, 0x18000
	v_add_u32_e32 v112, s47, v173
	s_add_i32 s48, 0, 0x1c000
	ds_read_b128 v[130:133], v112
	ds_read_b128 v[134:137], v112 offset:1024
	ds_read_b128 v[138:141], v112 offset:2048
	ds_read_b128 v[142:145], v112 offset:3072
	v_add_u32_e32 v112, s48, v173
	ds_read_b128 v[146:149], v112
	ds_read_b128 v[150:153], v112 offset:1024
	ds_read_b128 v[192:195], v112 offset:2048
	ds_read_b128 v[206:209], v112 offset:3072
	s_add_u32 s42, s42, 0x40000
	s_addc_u32 s43, s43, 0
	s_mov_b32 m0, s55
	v_lshl_add_u64 v[248:249], s[42:43], 0, v[154:155]
	ds_read_b128 v[210:213], v202 offset:32768
	ds_read_b128 v[214:217], v202 offset:33792
	ds_read_b128 v[218:221], v202 offset:34816
	ds_read_b128 v[222:225], v202 offset:35840
	ds_read_b128 v[226:229], v202 offset:36864
	ds_read_b128 v[230:233], v202 offset:37888
	ds_read_b128 v[234:237], v202 offset:38912
	ds_read_b128 v[238:241], v202 offset:39936
	global_load_lds_dwordx4 v[248:249], off
	v_lshl_add_u64 v[248:249], s[42:43], 0, v[158:159]
	s_mov_b32 m0, s56
	s_nop 0
	global_load_lds_dwordx4 v[248:249], off
	s_waitcnt vmcnt(8)
	s_waitcnt lgkmcnt(0)
	s_barrier
	s_waitcnt lgkmcnt(0)
	v_mfma_f32_16x16x32_bf16 v[118:121], v[130:133], v[210:213], v[118:121]
	v_mfma_f32_16x16x32_bf16 v[114:117], v[138:141], v[210:213], v[114:117]
	v_mfma_f32_16x16x32_bf16 v[104:107], v[130:133], v[218:221], v[104:107]
	v_mfma_f32_16x16x32_bf16 v[96:99], v[138:141], v[218:221], v[96:99]
	v_mfma_f32_16x16x32_bf16 v[88:91], v[130:133], v[226:229], v[88:91]
	v_mfma_f32_16x16x32_bf16 v[80:83], v[138:141], v[226:229], v[80:83]
	v_mfma_f32_16x16x32_bf16 v[72:75], v[130:133], v[234:237], v[72:75]
	v_mfma_f32_16x16x32_bf16 v[64:67], v[138:141], v[234:237], v[64:67]
	v_mfma_f32_16x16x32_bf16 v[118:121], v[134:137], v[214:217], v[118:121]
	v_mfma_f32_16x16x32_bf16 v[114:117], v[142:145], v[214:217], v[114:117]
	v_mfma_f32_16x16x32_bf16 v[104:107], v[134:137], v[222:225], v[104:107]
	v_mfma_f32_16x16x32_bf16 v[96:99], v[142:145], v[222:225], v[96:99]
	v_mfma_f32_16x16x32_bf16 v[88:91], v[134:137], v[230:233], v[88:91]
	v_mfma_f32_16x16x32_bf16 v[80:83], v[142:145], v[230:233], v[80:83]
	v_mfma_f32_16x16x32_bf16 v[72:75], v[134:137], v[238:241], v[72:75]
	v_mfma_f32_16x16x32_bf16 v[64:67], v[142:145], v[238:241], v[64:67]
	v_mfma_f32_16x16x32_bf16 v[126:129], v[146:149], v[210:213], v[126:129]
	v_mfma_f32_16x16x32_bf16 v[122:125], v[192:195], v[210:213], v[122:125]
	v_mfma_f32_16x16x32_bf16 v[108:111], v[146:149], v[218:221], v[108:111]
	v_mfma_f32_16x16x32_bf16 v[100:103], v[192:195], v[218:221], v[100:103]
	v_mfma_f32_16x16x32_bf16 v[92:95], v[146:149], v[226:229], v[92:95]
	v_mfma_f32_16x16x32_bf16 v[84:87], v[192:195], v[226:229], v[84:87]
	v_mfma_f32_16x16x32_bf16 v[76:79], v[146:149], v[234:237], v[76:79]
	v_mfma_f32_16x16x32_bf16 v[68:71], v[192:195], v[234:237], v[68:71]
	v_mfma_f32_16x16x32_bf16 v[126:129], v[150:153], v[214:217], v[126:129]
	v_mfma_f32_16x16x32_bf16 v[122:125], v[206:209], v[214:217], v[122:125]
	v_mfma_f32_16x16x32_bf16 v[108:111], v[150:153], v[222:225], v[108:111]
	v_mfma_f32_16x16x32_bf16 v[100:103], v[206:209], v[222:225], v[100:103]
	v_mfma_f32_16x16x32_bf16 v[92:95], v[150:153], v[230:233], v[92:95]
	v_mfma_f32_16x16x32_bf16 v[84:87], v[206:209], v[230:233], v[84:87]
	v_mfma_f32_16x16x32_bf16 v[76:79], v[150:153], v[238:241], v[76:79]
	v_mfma_f32_16x16x32_bf16 v[68:71], v[206:209], v[238:241], v[68:71]
	s_barrier
; #define PG8_STAGE(bufoff, gbase, voff) do { _Pragma("unroll") for (int _i = 0; _i < 2; ++_i) \
;         __builtin_amdgcn_global_load_lds((const unsigned*)((const char*)(gbase) + (voff)[_i]), (PG8_LAS unsigned*)(lds + (bufoff) + ldsw + _i * 8192), 16, 0, 0); } while (0)
; #define PG8_LDA(dst, b, h) do { _Pragma("unroll") for (int m = 0; m < 4; ++m) _Pragma("unroll") for (int k = 0; k < 2; ++k) dst[m][k] = *(const PG8_LAS bf16x8*)(lds + PG8_SA(b, h) + aoff + m * 2048 + k * 1024); } while (0)
; #define PG8_MMA(ai, bj, At, Bt) do { __builtin_amdgcn_s_setprio(1); _Pragma("unroll") for (int m = 0; m < 4; ++m) _Pragma("unroll") for (int n = 0; n < 2; ++n) _Pragma("unroll") for (int k = 0; k < 2; ++k) \
;         acc[ai][bj][m][n] = __builtin_amdgcn_mfma_f32_16x16x32_bf16(Bt[n][k], At[m][k], acc[ai][bj][m][n], 0, 0, 0); __builtin_amdgcn_s_setprio(0); } while (0)
; #define PG8_WAIT_V(n) asm volatile("s_waitcnt vmcnt(" #n ")" ::: "memory")
; #define PG8_WAIT_L(n) asm volatile("s_waitcnt lgkmcnt(" #n ")" ::: "memory")
; #define PG8_BAR __builtin_amdgcn_s_barrier()
; #define PG8_SCHED __builtin_amdgcn_sched_barrier(0)
; template <class Epi, class Sched, bool ALIGN_EPI = false, bool SP2 = false>
; __device__ __forceinline__ void gemm_phase(PG8_LAS unsigned char* lds, const Gemm g, const Sched& S, const Epi& E) {
;     ...
;             PG8_LDA(At, 1, 1); PG8_STAGE(PG8_SB(1, 0), b3, voffB); PG8_STAGE(PG8_SB(1, 1), b3 + hstep, voffB); PG8_STAGE(PG8_SA(1, 0), a3, voffA);
;             PG8_WAIT_V(8); PG8_WAIT_L(0); PG8_BAR; PG8_MMA(1, 0, At, B0); PG8_MMA(1, 1, At, B1); PG8_BAR; PG8_SCHED;
	s_add_i32 s42, s47, s1
	v_lshl_add_u64 v[170:171], v[170:171], 0, s[2:3]
	s_mov_b32 m0, s42
	ds_read_b128 v[210:213], v202 offset:49152
	ds_read_b128 v[214:217], v202 offset:50176
	ds_read_b128 v[218:221], v202 offset:51200
	ds_read_b128 v[222:225], v202 offset:52224
	ds_read_b128 v[226:229], v202 offset:53248
	ds_read_b128 v[230:233], v202 offset:54272
	ds_read_b128 v[234:237], v202 offset:55296
	ds_read_b128 v[238:241], v202 offset:56320
	global_load_lds_dwordx4 v[170:171], off
	s_add_i32 m0, s42, 0x2000
	s_add_u32 s30, s30, 0x40080
	v_lshl_add_u64 v[170:171], v[242:243], 0, s[2:3]
	s_addc_u32 s31, s31, 0
	s_add_i32 s42, s48, s1
	global_load_lds_dwordx4 v[170:171], off
	v_lshl_add_u64 v[170:171], s[30:31], 0, v[156:157]
	s_mov_b32 m0, s42
	s_nop 0
	global_load_lds_dwordx4 v[170:171], off
	v_lshl_add_u64 v[170:171], s[30:31], 0, v[160:161]
	s_add_i32 m0, s42, 0x2000
	s_nop 0
	global_load_lds_dwordx4 v[170:171], off
	v_lshl_add_u64 v[170:171], v[244:245], 0, s[2:3]
	s_mov_b32 m0, s57
	s_nop 0
	global_load_lds_dwordx4 v[170:171], off
	v_lshl_add_u64 v[170:171], v[246:247], 0, s[2:3]
	s_mov_b32 m0, s58
	s_nop 0
	global_load_lds_dwordx4 v[170:171], off
	s_waitcnt vmcnt(8)
	s_waitcnt lgkmcnt(0)
	s_barrier
	s_waitcnt lgkmcnt(0)
	v_mfma_f32_16x16x32_bf16 v[56:59], v[130:133], v[210:213], v[56:59]
	v_mfma_f32_16x16x32_bf16 v[48:51], v[138:141], v[210:213], v[48:51]
	v_mfma_f32_16x16x32_bf16 v[40:43], v[130:133], v[218:221], v[40:43]
	v_mfma_f32_16x16x32_bf16 v[32:35], v[138:141], v[218:221], v[32:35]
	v_mfma_f32_16x16x32_bf16 v[24:27], v[130:133], v[226:229], v[24:27]
	v_mfma_f32_16x16x32_bf16 v[16:19], v[138:141], v[226:229], v[16:19]
	v_mfma_f32_16x16x32_bf16 v[12:15], v[130:133], v[234:237], v[12:15]
	v_mfma_f32_16x16x32_bf16 v[8:11], v[138:141], v[234:237], v[8:11]
	v_mfma_f32_16x16x32_bf16 v[56:59], v[134:137], v[214:217], v[56:59]
	v_mfma_f32_16x16x32_bf16 v[48:51], v[142:145], v[214:217], v[48:51]
	v_mfma_f32_16x16x32_bf16 v[40:43], v[134:137], v[222:225], v[40:43]
	v_mfma_f32_16x16x32_bf16 v[32:35], v[142:145], v[222:225], v[32:35]
	v_mfma_f32_16x16x32_bf16 v[24:27], v[134:137], v[230:233], v[24:27]
	v_mfma_f32_16x16x32_bf16 v[16:19], v[142:145], v[230:233], v[16:19]
	v_mfma_f32_16x16x32_bf16 v[12:15], v[134:137], v[238:241], v[12:15]
	v_mfma_f32_16x16x32_bf16 v[8:11], v[142:145], v[238:241], v[8:11]
	v_mfma_f32_16x16x32_bf16 v[60:63], v[146:149], v[210:213], v[60:63]
	v_mfma_f32_16x16x32_bf16 v[52:55], v[192:195], v[210:213], v[52:55]
	v_mfma_f32_16x16x32_bf16 v[44:47], v[146:149], v[218:221], v[44:47]
	v_mfma_f32_16x16x32_bf16 v[36:39], v[192:195], v[218:221], v[36:39]
	v_mfma_f32_16x16x32_bf16 v[28:31], v[146:149], v[226:229], v[28:31]
	v_mfma_f32_16x16x32_bf16 v[20:23], v[192:195], v[226:229], v[20:23]
	v_mfma_f32_16x16x32_bf16 v[4:7], v[146:149], v[234:237], v[4:7]
	v_mfma_f32_16x16x32_bf16 v[0:3], v[192:195], v[234:237], v[0:3]
	v_mfma_f32_16x16x32_bf16 v[60:63], v[150:153], v[214:217], v[60:63]
	v_mfma_f32_16x16x32_bf16 v[52:55], v[206:209], v[214:217], v[52:55]
	v_mfma_f32_16x16x32_bf16 v[44:47], v[150:153], v[222:225], v[44:47]
	v_mfma_f32_16x16x32_bf16 v[36:39], v[206:209], v[222:225], v[36:39]
	v_mfma_f32_16x16x32_bf16 v[28:31], v[150:153], v[230:233], v[28:31]
	v_mfma_f32_16x16x32_bf16 v[20:23], v[206:209], v[230:233], v[20:23]
	v_mfma_f32_16x16x32_bf16 v[4:7], v[150:153], v[238:241], v[4:7]
	v_mfma_f32_16x16x32_bf16 v[0:3], v[206:209], v[238:241], v[0:3]
	s_barrier
	s_add_i32 s46, s46, 2
	s_add_u32 s28, s28, 0x100
	s_addc_u32 s29, s29, 0
	s_add_u32 s44, s44, 0x100
	s_addc_u32 s45, s45, 0
	s_cmp_gt_u32 s46, 13
	s_cbranch_scc0 .LBB0_300
	s_and_b64 vcc, exec, s[16:17]
	s_cbranch_vccz .LBB0_303
	s_barrier

; #define PG8_STAGE(bufoff, gbase, voff) do { _Pragma("unroll") for (int _i = 0; _i < 2; ++_i) \
;         __builtin_amdgcn_global_load_lds((const unsigned*)((const char*)(gbase) + (voff)[_i]), (PG8_LAS unsigned*)(lds + (bufoff) + ldsw + _i * 8192), 16, 0, 0); } while (0)
; #define PG8_LDA(dst, b, h) do { _Pragma("unroll") for (int m = 0; m < 4; ++m) _Pragma("unroll") for (int k = 0; k < 2; ++k) dst[m][k] = *(const PG8_LAS bf16x8*)(lds + PG8_SA(b, h) + aoff + m * 2048 + k * 1024); } while (0)
; #define PG8_LDB(dst, b, h) do { _Pragma("unroll") for (int n = 0; n < 2; ++n) _Pragma("unroll") for (int k = 0; k < 2; ++k) dst[n][k] = *(const PG8_LAS bf16x8*)(lds + PG8_SB(b, h) + boff + n * 2048 + k * 1024); } while (0)
; #define PG8_MMA(ai, bj, At, Bt) do { __builtin_amdgcn_s_setprio(1); _Pragma("unroll") for (int m = 0; m < 4; ++m) _Pragma("unroll") for (int n = 0; n < 2; ++n) _Pragma("unroll") for (int k = 0; k < 2; ++k) \
;         acc[ai][bj][m][n] = __builtin_amdgcn_mfma_f32_16x16x32_bf16(Bt[n][k], At[m][k], acc[ai][bj][m][n], 0, 0, 0); __builtin_amdgcn_s_setprio(0); } while (0)
; #define PG8_WAIT_V(n) asm volatile("s_waitcnt vmcnt(" #n ")" ::: "memory")
; #define PG8_WAIT_L(n) asm volatile("s_waitcnt lgkmcnt(" #n ")" ::: "memory")
; #define PG8_BAR __builtin_amdgcn_s_barrier()
; #define PG8_SCHED __builtin_amdgcn_sched_barrier(0)
; template <class Epi, class Sched, bool ALIGN_EPI = false, bool SP2 = false>
; __device__ __forceinline__ void gemm_phase(PG8_LAS unsigned char* lds, const Gemm g, const Sched& S, const Epi& E) {
;     ...
;             PG8_LDB(B0, 0, 0); PG8_LDB(B1, 0, 1); PG8_SCHED; PG8_LDA(At, 0, 0); PG8_STAGE(PG8_SA(1, 1), a1 + hstep, voffA);
;             PG8_WAIT_V(8); PG8_WAIT_L(0); PG8_BAR; PG8_MMA(0, 0, At, B0); PG8_MMA(0, 1, At, B1); PG8_BAR; PG8_SCHED;
;             PG8_LDA(At, 0, 1); PG8_STAGE(PG8_SB(0, 0), b2, voffB); PG8_STAGE(PG8_SB(0, 1), b2 + hstep, voffB); PG8_STAGE(PG8_SA(0, 0), a2, voffA);
.LBB0_587:
	s_add_u32 s28, s26, 0xfffc0080
	s_addc_u32 s29, s27, -1
	s_add_i32 s54, 0, 0x10000
	s_cmp_eq_u32 s53, 12
	s_cselect_b32 s31, s21, s29
	s_cselect_b32 s30, s49, s28
	s_cselect_b32 s29, s19, s52
	s_cselect_b32 s28, s50, s51
	s_add_i32 s56, 0, 0x14000
	v_add_u32_e32 v152, s54, v171
	v_add_u32_e32 v168, s56, v171
	ds_read_b128 v[130:133], v152
	ds_read_b128 v[134:137], v152 offset:1024
	ds_read_b128 v[148:151], v152 offset:2048
	ds_read_b128 v[152:155], v152 offset:3072
	ds_read_b128 v[156:159], v168
	ds_read_b128 v[160:163], v168 offset:1024
	ds_read_b128 v[164:167], v168 offset:2048
	ds_read_b128 v[182:185], v168 offset:3072
	v_lshl_add_u64 v[168:169], s[26:27], 0, v[144:145]
	s_add_i32 m0, s40, 0xc000
	ds_read_b128 v[190:193], v180
	ds_read_b128 v[202:205], v180 offset:1024
	ds_read_b128 v[206:209], v180 offset:2048
	ds_read_b128 v[210:213], v180 offset:3072
	ds_read_b128 v[214:217], v180 offset:4096
	ds_read_b128 v[218:221], v180 offset:5120
	ds_read_b128 v[222:225], v180 offset:6144
	ds_read_b128 v[226:229], v180 offset:7168
	global_load_lds_dwordx4 v[168:169], off
	v_lshl_add_u64 v[168:169], s[26:27], 0, v[146:147]
	s_add_i32 m0, s40, 0xe000
	s_nop 0
	global_load_lds_dwordx4 v[168:169], off
	s_waitcnt vmcnt(8)
	s_waitcnt lgkmcnt(0)
	s_barrier
	s_waitcnt lgkmcnt(0)
	v_mfma_f32_16x16x32_bf16 v[126:129], v[130:133], v[190:193], v[126:129]
	v_mfma_f32_16x16x32_bf16 v[122:125], v[148:151], v[190:193], v[122:125]
	v_mfma_f32_16x16x32_bf16 v[108:111], v[130:133], v[206:209], v[108:111]
	v_mfma_f32_16x16x32_bf16 v[104:107], v[148:151], v[206:209], v[104:107]
	v_mfma_f32_16x16x32_bf16 v[92:95], v[130:133], v[214:217], v[92:95]
	v_mfma_f32_16x16x32_bf16 v[88:91], v[148:151], v[214:217], v[88:91]
	v_mfma_f32_16x16x32_bf16 v[76:79], v[130:133], v[222:225], v[76:79]
	v_mfma_f32_16x16x32_bf16 v[72:75], v[148:151], v[222:225], v[72:75]
	v_mfma_f32_16x16x32_bf16 v[126:129], v[134:137], v[202:205], v[126:129]
	v_mfma_f32_16x16x32_bf16 v[122:125], v[152:155], v[202:205], v[122:125]
	v_mfma_f32_16x16x32_bf16 v[108:111], v[134:137], v[210:213], v[108:111]
	v_mfma_f32_16x16x32_bf16 v[104:107], v[152:155], v[210:213], v[104:107]
	v_mfma_f32_16x16x32_bf16 v[92:95], v[134:137], v[218:221], v[92:95]
	v_mfma_f32_16x16x32_bf16 v[88:91], v[152:155], v[218:221], v[88:91]
	v_mfma_f32_16x16x32_bf16 v[76:79], v[134:137], v[226:229], v[76:79]
	v_mfma_f32_16x16x32_bf16 v[72:75], v[152:155], v[226:229], v[72:75]
	v_mfma_f32_16x16x32_bf16 v[118:121], v[156:159], v[190:193], v[118:121]
	v_mfma_f32_16x16x32_bf16 v[114:117], v[164:167], v[190:193], v[114:117]
	v_mfma_f32_16x16x32_bf16 v[100:103], v[156:159], v[206:209], v[100:103]
	v_mfma_f32_16x16x32_bf16 v[96:99], v[164:167], v[206:209], v[96:99]
	v_mfma_f32_16x16x32_bf16 v[84:87], v[156:159], v[214:217], v[84:87]
	v_mfma_f32_16x16x32_bf16 v[80:83], v[164:167], v[214:217], v[80:83]
	v_mfma_f32_16x16x32_bf16 v[68:71], v[156:159], v[222:225], v[68:71]
	v_mfma_f32_16x16x32_bf16 v[64:67], v[164:167], v[222:225], v[64:67]
	v_mfma_f32_16x16x32_bf16 v[118:121], v[160:163], v[202:205], v[118:121]
	v_mfma_f32_16x16x32_bf16 v[114:117], v[182:185], v[202:205], v[114:117]
	v_mfma_f32_16x16x32_bf16 v[100:103], v[160:163], v[210:213], v[100:103]
	v_mfma_f32_16x16x32_bf16 v[96:99], v[182:185], v[210:213], v[96:99]
	v_mfma_f32_16x16x32_bf16 v[84:87], v[160:163], v[218:221], v[84:87]
	v_mfma_f32_16x16x32_bf16 v[80:83], v[182:185], v[218:221], v[80:83]
	v_mfma_f32_16x16x32_bf16 v[68:71], v[160:163], v[226:229], v[68:71]
	v_mfma_f32_16x16x32_bf16 v[64:67], v[182:185], v[226:229], v[64:67]
	s_barrier
	s_add_i32 s54, s54, s35
	v_lshl_add_u64 v[168:169], s[28:29], 0, v[112:113]
	s_mov_b32 m0, s54
	ds_read_b128 v[190:193], v180 offset:16384
	ds_read_b128 v[202:205], v180 offset:17408
	ds_read_b128 v[206:209], v180 offset:18432
	ds_read_b128 v[210:213], v180 offset:19456
	ds_read_b128 v[214:217], v180 offset:20480
	ds_read_b128 v[218:221], v180 offset:21504
	ds_read_b128 v[222:225], v180 offset:22528
	ds_read_b128 v[226:229], v180 offset:23552
	global_load_lds_dwordx4 v[168:169], off
	s_add_i32 m0, s54, 0x2000
	s_add_u32 s54, s28, 0x40000
	v_lshl_add_u64 v[194:195], s[28:29], 0, v[138:139]
	s_addc_u32 s55, s29, 0
	s_add_i32 s56, s56, s35
	global_load_lds_dwordx4 v[194:195], off
	v_lshl_add_u64 v[230:231], s[54:55], 0, v[112:113]
	s_mov_b32 m0, s56
	v_lshl_add_u64 v[232:233], s[30:31], 0, v[140:141]
	global_load_lds_dwordx4 v[230:231], off
	v_lshl_add_u64 v[230:231], s[54:55], 0, v[138:139]
	s_add_i32 m0, s56, 0x2000
	s_nop 0
	global_load_lds_dwordx4 v[230:231], off
	v_lshl_add_u64 v[230:231], s[30:31], 0, v[142:143]
	s_mov_b32 m0, s40
	s_nop 0
	global_load_lds_dwordx4 v[230:231], off
	s_mov_b32 m0, s41
	s_nop 0
	global_load_lds_dwordx4 v[232:233], off
	s_waitcnt vmcnt(8)
	s_waitcnt lgkmcnt(0)
	s_barrier
; #define PG8_STAGE(bufoff, gbase, voff) do { _Pragma("unroll") for (int _i = 0; _i < 2; ++_i) \
;         __builtin_amdgcn_global_load_lds((const unsigned*)((const char*)(gbase) + (voff)[_i]), (PG8_LAS unsigned*)(lds + (bufoff) + ldsw + _i * 8192), 16, 0, 0); } while (0)
; #define PG8_LDA(dst, b, h) do { _Pragma("unroll") for (int m = 0; m < 4; ++m) _Pragma("unroll") for (int k = 0; k < 2; ++k) dst[m][k] = *(const PG8_LAS bf16x8*)(lds + PG8_SA(b, h) + aoff + m * 2048 + k * 1024); } while (0)
; #define PG8_LDB(dst, b, h) do { _Pragma("unroll") for (int n = 0; n < 2; ++n) _Pragma("unroll") for (int k = 0; k < 2; ++k) dst[n][k] = *(const PG8_LAS bf16x8*)(lds + PG8_SB(b, h) + boff + n * 2048 + k * 1024); } while (0)
; #define PG8_MMA(ai, bj, At, Bt) do { __builtin_amdgcn_s_setprio(1); _Pragma("unroll") for (int m = 0; m < 4; ++m) _Pragma("unroll") for (int n = 0; n < 2; ++n) _Pragma("unroll") for (int k = 0; k < 2; ++k) \
;         acc[ai][bj][m][n] = __builtin_amdgcn_mfma_f32_16x16x32_bf16(Bt[n][k], At[m][k], acc[ai][bj][m][n], 0, 0, 0); __builtin_amdgcn_s_setprio(0); } while (0)
; #define PG8_WAIT_V(n) asm volatile("s_waitcnt vmcnt(" #n ")" ::: "memory")
; #define PG8_WAIT_L(n) asm volatile("s_waitcnt lgkmcnt(" #n ")" ::: "memory")
; #define PG8_BAR __builtin_amdgcn_s_barrier()
; #define PG8_SCHED __builtin_amdgcn_sched_barrier(0)
; template <class Epi, class Sched, bool ALIGN_EPI = false, bool SP2 = false>
; __device__ __forceinline__ void gemm_phase(PG8_LAS unsigned char* lds, const Gemm g, const Sched& S, const Epi& E) {
;     ...
;             PG8_WAIT_V(8); PG8_WAIT_L(0); PG8_BAR; PG8_MMA(1, 0, At, B0); PG8_MMA(1, 1, At, B1); PG8_BAR; PG8_SCHED;
;             PG8_LDB(B0, 1, 0); PG8_LDB(B1, 1, 1); PG8_SCHED; PG8_LDA(At, 1, 0); PG8_STAGE(PG8_SA(0, 1), a2 + hstep, voffA);
;             PG8_WAIT_V(8); PG8_WAIT_L(0); PG8_BAR; PG8_MMA(0, 0, At, B0); PG8_MMA(0, 1, At, B1); PG8_BAR; PG8_SCHED;
	s_waitcnt lgkmcnt(0)
	v_mfma_f32_16x16x32_bf16 v[60:63], v[130:133], v[190:193], v[60:63]
	v_mfma_f32_16x16x32_bf16 v[56:59], v[148:151], v[190:193], v[56:59]
	v_mfma_f32_16x16x32_bf16 v[44:47], v[130:133], v[206:209], v[44:47]
	v_mfma_f32_16x16x32_bf16 v[40:43], v[148:151], v[206:209], v[40:43]
	v_mfma_f32_16x16x32_bf16 v[28:31], v[130:133], v[214:217], v[28:31]
	v_mfma_f32_16x16x32_bf16 v[24:27], v[148:151], v[214:217], v[24:27]
	v_mfma_f32_16x16x32_bf16 v[12:15], v[130:133], v[222:225], v[12:15]
	v_mfma_f32_16x16x32_bf16 v[8:11], v[148:151], v[222:225], v[8:11]
	v_mfma_f32_16x16x32_bf16 v[60:63], v[134:137], v[202:205], v[60:63]
	v_mfma_f32_16x16x32_bf16 v[56:59], v[152:155], v[202:205], v[56:59]
	v_mfma_f32_16x16x32_bf16 v[44:47], v[134:137], v[210:213], v[44:47]
	v_mfma_f32_16x16x32_bf16 v[40:43], v[152:155], v[210:213], v[40:43]
	v_mfma_f32_16x16x32_bf16 v[28:31], v[134:137], v[218:221], v[28:31]
	v_mfma_f32_16x16x32_bf16 v[24:27], v[152:155], v[218:221], v[24:27]
	v_mfma_f32_16x16x32_bf16 v[12:15], v[134:137], v[226:229], v[12:15]
	v_mfma_f32_16x16x32_bf16 v[8:11], v[152:155], v[226:229], v[8:11]
	v_mfma_f32_16x16x32_bf16 v[52:55], v[156:159], v[190:193], v[52:55]
	v_mfma_f32_16x16x32_bf16 v[48:51], v[164:167], v[190:193], v[48:51]
	v_mfma_f32_16x16x32_bf16 v[36:39], v[156:159], v[206:209], v[36:39]
	v_mfma_f32_16x16x32_bf16 v[32:35], v[164:167], v[206:209], v[32:35]
	v_mfma_f32_16x16x32_bf16 v[20:23], v[156:159], v[214:217], v[20:23]
	v_mfma_f32_16x16x32_bf16 v[16:19], v[164:167], v[214:217], v[16:19]
	v_mfma_f32_16x16x32_bf16 v[4:7], v[156:159], v[222:225], v[4:7]
	v_mfma_f32_16x16x32_bf16 v[0:3], v[164:167], v[222:225], v[0:3]
	v_mfma_f32_16x16x32_bf16 v[52:55], v[160:163], v[202:205], v[52:55]
	v_mfma_f32_16x16x32_bf16 v[48:51], v[182:185], v[202:205], v[48:51]
	v_mfma_f32_16x16x32_bf16 v[36:39], v[160:163], v[210:213], v[36:39]
	v_mfma_f32_16x16x32_bf16 v[32:35], v[182:185], v[210:213], v[32:35]
	v_mfma_f32_16x16x32_bf16 v[20:23], v[160:163], v[218:221], v[20:23]
	v_mfma_f32_16x16x32_bf16 v[16:19], v[182:185], v[218:221], v[16:19]
	v_mfma_f32_16x16x32_bf16 v[4:7], v[160:163], v[226:229], v[4:7]
	v_mfma_f32_16x16x32_bf16 v[0:3], v[182:185], v[226:229], v[0:3]
	s_barrier
	s_add_i32 s54, 0, 0x18000
	s_add_i32 s55, 0, 0x1c000
	v_add_u32_e32 v152, s54, v171
	v_add_u32_e32 v181, s55, v171
	ds_read_b128 v[130:133], v152
	ds_read_b128 v[134:137], v152 offset:1024
	ds_read_b128 v[148:151], v152 offset:2048
	ds_read_b128 v[152:155], v152 offset:3072
	ds_read_b128 v[156:159], v181
	ds_read_b128 v[160:163], v181 offset:1024
	ds_read_b128 v[164:167], v181 offset:2048
	ds_read_b128 v[182:185], v181 offset:3072
	s_add_u32 s30, s30, 0x40000
	s_addc_u32 s31, s31, 0
	s_mov_b32 m0, s42
	v_lshl_add_u64 v[234:235], s[30:31], 0, v[142:143]
	ds_read_b128 v[190:193], v180 offset:32768
	ds_read_b128 v[202:205], v180 offset:33792
	ds_read_b128 v[206:209], v180 offset:34816
	ds_read_b128 v[210:213], v180 offset:35840
	ds_read_b128 v[214:217], v180 offset:36864
	ds_read_b128 v[218:221], v180 offset:37888
	ds_read_b128 v[222:225], v180 offset:38912
	ds_read_b128 v[226:229], v180 offset:39936
	global_load_lds_dwordx4 v[234:235], off
	v_lshl_add_u64 v[234:235], s[30:31], 0, v[140:141]
	s_mov_b32 m0, s43
	s_nop 0
	global_load_lds_dwordx4 v[234:235], off
	s_waitcnt vmcnt(8)
	s_waitcnt lgkmcnt(0)
	s_barrier
	s_waitcnt lgkmcnt(0)
	v_mfma_f32_16x16x32_bf16 v[126:129], v[130:133], v[190:193], v[126:129]
	v_mfma_f32_16x16x32_bf16 v[122:125], v[148:151], v[190:193], v[122:125]
	v_mfma_f32_16x16x32_bf16 v[108:111], v[130:133], v[206:209], v[108:111]
	v_mfma_f32_16x16x32_bf16 v[104:107], v[148:151], v[206:209], v[104:107]
	v_mfma_f32_16x16x32_bf16 v[92:95], v[130:133], v[214:217], v[92:95]
	v_mfma_f32_16x16x32_bf16 v[88:91], v[148:151], v[214:217], v[88:91]
	v_mfma_f32_16x16x32_bf16 v[76:79], v[130:133], v[222:225], v[76:79]
	v_mfma_f32_16x16x32_bf16 v[72:75], v[148:151], v[222:225], v[72:75]
	v_mfma_f32_16x16x32_bf16 v[126:129], v[134:137], v[202:205], v[126:129]
	v_mfma_f32_16x16x32_bf16 v[122:125], v[152:155], v[202:205], v[122:125]
	v_mfma_f32_16x16x32_bf16 v[108:111], v[134:137], v[210:213], v[108:111]
	v_mfma_f32_16x16x32_bf16 v[104:107], v[152:155], v[210:213], v[104:107]
	v_mfma_f32_16x16x32_bf16 v[92:95], v[134:137], v[218:221], v[92:95]
	v_mfma_f32_16x16x32_bf16 v[88:91], v[152:155], v[218:221], v[88:91]
	v_mfma_f32_16x16x32_bf16 v[76:79], v[134:137], v[226:229], v[76:79]
	v_mfma_f32_16x16x32_bf16 v[72:75], v[152:155], v[226:229], v[72:75]
	v_mfma_f32_16x16x32_bf16 v[118:121], v[156:159], v[190:193], v[118:121]
	v_mfma_f32_16x16x32_bf16 v[114:117], v[164:167], v[190:193], v[114:117]
	v_mfma_f32_16x16x32_bf16 v[100:103], v[156:159], v[206:209], v[100:103]
	v_mfma_f32_16x16x32_bf16 v[96:99], v[164:167], v[206:209], v[96:99]
	v_mfma_f32_16x16x32_bf16 v[84:87], v[156:159], v[214:217], v[84:87]
	v_mfma_f32_16x16x32_bf16 v[80:83], v[164:167], v[214:217], v[80:83]
	v_mfma_f32_16x16x32_bf16 v[68:71], v[156:159], v[222:225], v[68:71]
	v_mfma_f32_16x16x32_bf16 v[64:67], v[164:167], v[222:225], v[64:67]
	v_mfma_f32_16x16x32_bf16 v[118:121], v[160:163], v[202:205], v[118:121]
	v_mfma_f32_16x16x32_bf16 v[114:117], v[182:185], v[202:205], v[114:117]
	v_mfma_f32_16x16x32_bf16 v[100:103], v[160:163], v[210:213], v[100:103]
	v_mfma_f32_16x16x32_bf16 v[96:99], v[182:185], v[210:213], v[96:99]
	v_mfma_f32_16x16x32_bf16 v[84:87], v[160:163], v[218:221], v[84:87]
	v_mfma_f32_16x16x32_bf16 v[80:83], v[182:185], v[218:221], v[80:83]
	v_mfma_f32_16x16x32_bf16 v[68:71], v[160:163], v[226:229], v[68:71]
	v_mfma_f32_16x16x32_bf16 v[64:67], v[182:185], v[226:229], v[64:67]
	s_barrier
; #define PG8_STAGE(bufoff, gbase, voff) do { _Pragma("unroll") for (int _i = 0; _i < 2; ++_i) \
;         __builtin_amdgcn_global_load_lds((const unsigned*)((const char*)(gbase) + (voff)[_i]), (PG8_LAS unsigned*)(lds + (bufoff) + ldsw + _i * 8192), 16, 0, 0); } while (0)
; #define PG8_LDA(dst, b, h) do { _Pragma("unroll") for (int m = 0; m < 4; ++m) _Pragma("unroll") for (int k = 0; k < 2; ++k) dst[m][k] = *(const PG8_LAS bf16x8*)(lds + PG8_SA(b, h) + aoff + m * 2048 + k * 1024); } while (0)
; #define PG8_MMA(ai, bj, At, Bt) do { __builtin_amdgcn_s_setprio(1); _Pragma("unroll") for (int m = 0; m < 4; ++m) _Pragma("unroll") for (int n = 0; n < 2; ++n) _Pragma("unroll") for (int k = 0; k < 2; ++k) \
;         acc[ai][bj][m][n] = __builtin_amdgcn_mfma_f32_16x16x32_bf16(Bt[n][k], At[m][k], acc[ai][bj][m][n], 0, 0, 0); __builtin_amdgcn_s_setprio(0); } while (0)
; #define PG8_WAIT_V(n) asm volatile("s_waitcnt vmcnt(" #n ")" ::: "memory")
; #define PG8_WAIT_L(n) asm volatile("s_waitcnt lgkmcnt(" #n ")" ::: "memory")
; #define PG8_BAR __builtin_amdgcn_s_barrier()
; #define PG8_SCHED __builtin_amdgcn_sched_barrier(0)
; template <class Epi, class Sched, bool ALIGN_EPI = false, bool SP2 = false>
; __device__ __forceinline__ void gemm_phase(PG8_LAS unsigned char* lds, const Gemm g, const Sched& S, const Epi& E) {
;     ...
;             PG8_LDA(At, 1, 1); PG8_STAGE(PG8_SB(1, 0), b3, voffB); PG8_STAGE(PG8_SB(1, 1), b3 + hstep, voffB); PG8_STAGE(PG8_SA(1, 0), a3, voffA);
;             PG8_WAIT_V(8); PG8_WAIT_L(0); PG8_BAR; PG8_MMA(1, 0, At, B0); PG8_MMA(1, 1, At, B1); PG8_BAR; PG8_SCHED;
	s_add_i32 s30, s54, s35
	v_lshl_add_u64 v[168:169], v[168:169], 0, s[2:3]
	s_mov_b32 m0, s30
	ds_read_b128 v[190:193], v180 offset:49152
	ds_read_b128 v[202:205], v180 offset:50176
	ds_read_b128 v[206:209], v180 offset:51200
	ds_read_b128 v[210:213], v180 offset:52224
	ds_read_b128 v[214:217], v180 offset:53248
	ds_read_b128 v[218:221], v180 offset:54272
	ds_read_b128 v[222:225], v180 offset:55296
	ds_read_b128 v[226:229], v180 offset:56320
	global_load_lds_dwordx4 v[168:169], off
	s_add_i32 m0, s30, 0x2000
	s_add_u32 s28, s28, 0x40080
	v_lshl_add_u64 v[168:169], v[194:195], 0, s[2:3]
	s_addc_u32 s29, s29, 0
	s_add_i32 s30, s55, s35
	global_load_lds_dwordx4 v[168:169], off
	v_lshl_add_u64 v[168:169], s[28:29], 0, v[112:113]
	s_mov_b32 m0, s30
	s_nop 0
	global_load_lds_dwordx4 v[168:169], off
	v_lshl_add_u64 v[168:169], s[28:29], 0, v[138:139]
	s_add_i32 m0, s30, 0x2000
	s_nop 0
	global_load_lds_dwordx4 v[168:169], off
	v_lshl_add_u64 v[168:169], v[230:231], 0, s[2:3]
	s_mov_b32 m0, s45
	s_nop 0
	global_load_lds_dwordx4 v[168:169], off
	v_lshl_add_u64 v[168:169], v[232:233], 0, s[2:3]
	s_mov_b32 m0, s46
	s_nop 0
	global_load_lds_dwordx4 v[168:169], off
	s_waitcnt vmcnt(8)
	s_waitcnt lgkmcnt(0)
	s_barrier
	s_waitcnt lgkmcnt(0)
	v_mfma_f32_16x16x32_bf16 v[60:63], v[130:133], v[190:193], v[60:63]
	v_mfma_f32_16x16x32_bf16 v[56:59], v[148:151], v[190:193], v[56:59]
	v_mfma_f32_16x16x32_bf16 v[44:47], v[130:133], v[206:209], v[44:47]
	v_mfma_f32_16x16x32_bf16 v[40:43], v[148:151], v[206:209], v[40:43]
	v_mfma_f32_16x16x32_bf16 v[28:31], v[130:133], v[214:217], v[28:31]
	v_mfma_f32_16x16x32_bf16 v[24:27], v[148:151], v[214:217], v[24:27]
	v_mfma_f32_16x16x32_bf16 v[12:15], v[130:133], v[222:225], v[12:15]
	v_mfma_f32_16x16x32_bf16 v[8:11], v[148:151], v[222:225], v[8:11]
	v_mfma_f32_16x16x32_bf16 v[60:63], v[134:137], v[202:205], v[60:63]
	v_mfma_f32_16x16x32_bf16 v[56:59], v[152:155], v[202:205], v[56:59]
	v_mfma_f32_16x16x32_bf16 v[44:47], v[134:137], v[210:213], v[44:47]
	v_mfma_f32_16x16x32_bf16 v[40:43], v[152:155], v[210:213], v[40:43]
	v_mfma_f32_16x16x32_bf16 v[28:31], v[134:137], v[218:221], v[28:31]
	v_mfma_f32_16x16x32_bf16 v[24:27], v[152:155], v[218:221], v[24:27]
	v_mfma_f32_16x16x32_bf16 v[12:15], v[134:137], v[226:229], v[12:15]
	v_mfma_f32_16x16x32_bf16 v[8:11], v[152:155], v[226:229], v[8:11]
	v_mfma_f32_16x16x32_bf16 v[52:55], v[156:159], v[190:193], v[52:55]
	v_mfma_f32_16x16x32_bf16 v[48:51], v[164:167], v[190:193], v[48:51]
	v_mfma_f32_16x16x32_bf16 v[36:39], v[156:159], v[206:209], v[36:39]
	v_mfma_f32_16x16x32_bf16 v[32:35], v[164:167], v[206:209], v[32:35]
	v_mfma_f32_16x16x32_bf16 v[20:23], v[156:159], v[214:217], v[20:23]
	v_mfma_f32_16x16x32_bf16 v[16:19], v[164:167], v[214:217], v[16:19]
	v_mfma_f32_16x16x32_bf16 v[4:7], v[156:159], v[222:225], v[4:7]
	v_mfma_f32_16x16x32_bf16 v[0:3], v[164:167], v[222:225], v[0:3]
	v_mfma_f32_16x16x32_bf16 v[52:55], v[160:163], v[202:205], v[52:55]
	v_mfma_f32_16x16x32_bf16 v[48:51], v[182:185], v[202:205], v[48:51]
	v_mfma_f32_16x16x32_bf16 v[36:39], v[160:163], v[210:213], v[36:39]
	v_mfma_f32_16x16x32_bf16 v[32:35], v[182:185], v[210:213], v[32:35]
	v_mfma_f32_16x16x32_bf16 v[20:23], v[160:163], v[218:221], v[20:23]
	v_mfma_f32_16x16x32_bf16 v[16:19], v[182:185], v[218:221], v[16:19]
	v_mfma_f32_16x16x32_bf16 v[4:7], v[160:163], v[226:229], v[4:7]
	v_mfma_f32_16x16x32_bf16 v[0:3], v[182:185], v[226:229], v[0:3]
	s_barrier
	s_add_i32 s53, s53, 2
	s_add_u32 s26, s26, 0x100
	s_addc_u32 s27, s27, 0
	s_add_u32 s51, s51, 0x100
	s_addc_u32 s52, s52, 0
	s_cmp_gt_u32 s53, 13
	s_cbranch_scc0 .LBB0_587
	s_and_b64 vcc, exec, s[12:13]
	s_cbranch_vccz .LBB0_590
	s_barrier
